# code placement: the five GEMM K-loop heads aligned to 64 bytes (.p2align 6)
# speedup vs baseline: 1.0040x; 1.0040x over previous
; #define PG8_STAGE(bufoff, gbase, voff) do { _Pragma("unroll") for (int _i = 0; _i < 2; ++_i) \
;         __builtin_amdgcn_global_load_lds((const unsigned*)((const char*)(gbase) + (voff)[_i]), (PG8_LAS unsigned*)(lds + (bufoff) + ldsw + _i * 8192), 16, 0, 0); } while (0)
; #define PG8_LDA(dst, b, h) do { _Pragma("unroll") for (int m = 0; m < 4; ++m) _Pragma("unroll") for (int k = 0; k < 2; ++k) dst[m][k] = *(const PG8_LAS bf16x8*)(lds + PG8_SA(b, h) + aoff + m * 2048 + k * 1024); } while (0)
; #define PG8_LDB(dst, b, h) do { _Pragma("unroll") for (int n = 0; n < 2; ++n) _Pragma("unroll") for (int k = 0; k < 2; ++k) dst[n][k] = *(const PG8_LAS bf16x8*)(lds + PG8_SB(b, h) + boff + n * 2048 + k * 1024); } while (0)
; #define PG8_WAIT_V(n) asm volatile("s_waitcnt vmcnt(" #n ")" ::: "memory")
; #define PG8_WAIT_L(n) asm volatile("s_waitcnt lgkmcnt(" #n ")" ::: "memory")
; #define PG8_BAR __builtin_amdgcn_s_barrier()
; template <class Epi, class Sched, bool ALIGN_EPI = false, bool SP2 = false>
; __device__ __forceinline__ void gemm_phase(PG8_LAS unsigned char* lds, const Gemm g, const Sched& S, const Epi& E) {
;     ...
;         const bool has_next = S.next(ui + 1, nxt);
;         const char* nA = has_next ? (const char*)g.A + (size_t)nxt.pm * tstep : cA; const char* nB = has_next ? (const char*)g.Bt + (size_t)nxt.pn * tstep : cB;
;         for (int t = 0; t < nt; t += 2) {
;             if constexpr (Epi::HAS_MID) { if (t == (nt >> 1)) E.mid(acc, cur, wr, wc, fr, fq); }
;             const bool last = (t == nt - 2);
;             const char* a1 = cA + (size_t)(t + 1) * kstep;
;             const char* a2 = last ? nA : cA + (size_t)(t + 2) * kstep; const char* b2 = last ? nB : cB + (size_t)(t + 2) * kstep;
;             const char* a3 = a2 + kstep; const char* b3 = b2 + kstep;
;             if (last && has_next) S.a_ready(nxt);
;             if constexpr (SP2) {
;             PG8_LDB(B0, 0, 0); PG8_LDB(B1, 0, 1); PG8_SCHED; PG8_LDA(At, 0, 0); PG8_STAGE(PG8_SA(1, 1), a1 + hstep, voffA);
;             PG8_WAIT_V(8); PG8_WAIT_L(0); PG8_BAR; PG8_MMA(0, 0, At, B0); PG8_MMA(0, 1, At, B1); PG8_BAR; PG8_SCHED;
;             PG8_LDA(At, 0, 1); PG8_STAGE(PG8_SB(0, 0), b2, voffB); PG8_STAGE(PG8_SB(0, 1), b2 + hstepB, voffB); PG8_STAGE(PG8_SA(0, 0), a2, voffA);
;             PG8_WAIT_V(8); PG8_WAIT_L(0); PG8_BAR; PG8_MMA(1, 0, At, B0); PG8_MMA(1, 1, At, B1); PG8_BAR; PG8_SCHED;
.LBB0_149:
	s_ashr_i32 s17, s16, 31
	s_lshl_b64 s[18:19], s[16:17], 19
	s_add_u32 s18, s62, s18
	s_addc_u32 s19, s63, s19
	s_and_b64 s[20:21], s[4:5], exec
	s_cselect_b32 s17, s19, s25
	s_cselect_b32 s71, s18, s24
	s_ashr_i32 s15, s14, 31
	s_lshl_b64 s[20:21], s[14:15], 19
	s_add_u32 s20, s3, s20
	s_addc_u32 s21, s80, s21
	s_and_b64 s[28:29], s[4:5], exec
	s_cselect_b32 s15, s21, s27
	s_cselect_b32 s72, s20, s26
	s_add_u32 s24, s24, 0xc000
	s_addc_u32 s25, s25, 0
	s_add_u32 s73, s26, 0x10000
	s_addc_u32 s74, s27, 0
	s_mov_b32 s75, -2
	ds_read_b128 v[156:159], v150
	ds_read_b128 v[160:163], v150 offset:1024
	ds_read_b128 v[164:167], v150 offset:2048
	ds_read_b128 v[168:171], v150 offset:3072
	ds_read_b128 v[172:175], v151
	ds_read_b128 v[176:179], v151 offset:1024
	ds_read_b128 v[180:183], v151 offset:2048
	ds_read_b128 v[184:187], v151 offset:3072
	s_add_u32 s26, s24, 0x4000
	s_addc_u32 s27, s25, 0
	s_cmp_eq_u32 s75, 12
	s_cselect_b32 s40, s71, s26
	s_cselect_b32 s41, s17, s27
	s_cselect_b32 s28, s72, s73
	s_cselect_b32 s29, s15, s74
	s_add_u32 s26, s40, 0x8000
	s_addc_u32 s27, s41, 0
	s_add_i32 m0, s23, 0xc000
	ds_read_b128 v[188:191], v152
	ds_read_b128 v[192:195], v152 offset:1024
	ds_read_b128 v[196:199], v152 offset:2048
	ds_read_b128 v[200:203], v152 offset:3072
	ds_read_b128 v[204:207], v152 offset:4096
	ds_read_b128 v[208:211], v152 offset:5120
	ds_read_b128 v[212:215], v152 offset:6144
	ds_read_b128 v[220:223], v152 offset:7168
	global_load_lds_dwordx4 v140, s[24:25]
	s_add_i32 m0, s23, 0xe000
	s_nop 0
	global_load_lds_dwordx4 v142, s[24:25]
	s_waitcnt vmcnt(8)
	s_waitcnt lgkmcnt(0)
	s_setprio 1
	s_barrier
	v_mfma_f32_16x16x32_bf16 v[126:129], v[156:159], v[188:191], 0
	v_mfma_f32_16x16x32_bf16 v[122:125], v[164:167], v[188:191], 0
	v_mfma_f32_16x16x32_bf16 v[114:117], v[156:159], v[196:199], 0
	v_mfma_f32_16x16x32_bf16 v[106:109], v[164:167], v[196:199], 0
	v_mfma_f32_16x16x32_bf16 v[98:101], v[156:159], v[204:207], 0
	v_mfma_f32_16x16x32_bf16 v[90:93], v[164:167], v[204:207], 0
	v_mfma_f32_16x16x32_bf16 v[78:81], v[156:159], v[212:215], 0
	v_mfma_f32_16x16x32_bf16 v[74:77], v[164:167], v[212:215], 0
	v_mfma_f32_16x16x32_bf16 v[126:129], v[160:163], v[192:195], v[126:129]
	v_mfma_f32_16x16x32_bf16 v[122:125], v[168:171], v[192:195], v[122:125]
	v_mfma_f32_16x16x32_bf16 v[114:117], v[160:163], v[200:203], v[114:117]
	v_mfma_f32_16x16x32_bf16 v[106:109], v[168:171], v[200:203], v[106:109]
	v_mfma_f32_16x16x32_bf16 v[98:101], v[160:163], v[208:211], v[98:101]
	v_mfma_f32_16x16x32_bf16 v[90:93], v[168:171], v[208:211], v[90:93]
	v_mfma_f32_16x16x32_bf16 v[78:81], v[160:163], v[220:223], v[78:81]
	v_mfma_f32_16x16x32_bf16 v[74:77], v[168:171], v[220:223], v[74:77]
	s_setprio 0
	s_setprio 1
	v_mfma_f32_16x16x32_bf16 v[118:121], v[172:175], v[188:191], 0
	v_mfma_f32_16x16x32_bf16 v[110:113], v[180:183], v[188:191], 0
	v_mfma_f32_16x16x32_bf16 v[102:105], v[172:175], v[196:199], 0
	v_mfma_f32_16x16x32_bf16 v[94:97], v[180:183], v[196:199], 0
	v_mfma_f32_16x16x32_bf16 v[86:89], v[172:175], v[204:207], 0
	v_mfma_f32_16x16x32_bf16 v[82:85], v[180:183], v[204:207], 0
	v_mfma_f32_16x16x32_bf16 v[70:73], v[172:175], v[212:215], 0
	v_mfma_f32_16x16x32_bf16 v[66:69], v[180:183], v[212:215], 0
	v_mfma_f32_16x16x32_bf16 v[118:121], v[176:179], v[192:195], v[118:121]
	v_mfma_f32_16x16x32_bf16 v[110:113], v[184:187], v[192:195], v[110:113]
	v_mfma_f32_16x16x32_bf16 v[102:105], v[176:179], v[200:203], v[102:105]
	v_mfma_f32_16x16x32_bf16 v[94:97], v[184:187], v[200:203], v[94:97]
	v_mfma_f32_16x16x32_bf16 v[86:89], v[176:179], v[208:211], v[86:89]
	v_mfma_f32_16x16x32_bf16 v[82:85], v[184:187], v[208:211], v[82:85]
	v_mfma_f32_16x16x32_bf16 v[70:73], v[176:179], v[220:223], v[70:73]
	v_mfma_f32_16x16x32_bf16 v[66:69], v[184:187], v[220:223], v[66:69]
	s_barrier
	s_setprio 0
	s_add_i32 s76, s56, s0
	s_mov_b32 m0, s76
	ds_read_b128 v[188:191], v152 offset:16384
	ds_read_b128 v[192:195], v152 offset:17408
	ds_read_b128 v[196:199], v152 offset:18432
	ds_read_b128 v[200:203], v152 offset:19456
	ds_read_b128 v[204:207], v152 offset:20480
	ds_read_b128 v[208:211], v152 offset:21504
	ds_read_b128 v[212:215], v152 offset:22528
	ds_read_b128 v[220:223], v152 offset:23552
	global_load_lds_dwordx4 v134, s[28:29]
	s_add_i32 m0, s76, 0x2000
	s_add_u32 s76, s28, 0x1000
	s_addc_u32 s77, s29, 0
	s_add_i32 s78, s57, s0
	global_load_lds_dwordx4 v130, s[28:29]
	s_mov_b32 m0, s78
	s_nop 0
	global_load_lds_dwordx4 v134, s[76:77]
	s_add_i32 m0, s78, 0x2000
	s_nop 0
	global_load_lds_dwordx4 v130, s[76:77]
	s_mov_b32 m0, s23
	s_nop 0
	global_load_lds_dwordx4 v136, s[40:41]
	s_mov_b32 m0, s49
	s_nop 0
	global_load_lds_dwordx4 v132, s[40:41]
	s_waitcnt vmcnt(8)
	s_waitcnt lgkmcnt(0)
	s_setprio 1
	s_barrier
; #define PG8_STAGE(bufoff, gbase, voff) do { _Pragma("unroll") for (int _i = 0; _i < 2; ++_i) \
;         __builtin_amdgcn_global_load_lds((const unsigned*)((const char*)(gbase) + (voff)[_i]), (PG8_LAS unsigned*)(lds + (bufoff) + ldsw + _i * 8192), 16, 0, 0); } while (0)
; #define PG8_LDA(dst, b, h) do { _Pragma("unroll") for (int m = 0; m < 4; ++m) _Pragma("unroll") for (int k = 0; k < 2; ++k) dst[m][k] = *(const PG8_LAS bf16x8*)(lds + PG8_SA(b, h) + aoff + m * 2048 + k * 1024); } while (0)
; #define PG8_LDB(dst, b, h) do { _Pragma("unroll") for (int n = 0; n < 2; ++n) _Pragma("unroll") for (int k = 0; k < 2; ++k) dst[n][k] = *(const PG8_LAS bf16x8*)(lds + PG8_SB(b, h) + boff + n * 2048 + k * 1024); } while (0)
; #define PG8_MMA(ai, bj, At, Bt) do { __builtin_amdgcn_s_setprio(1); _Pragma("unroll") for (int m = 0; m < 4; ++m) _Pragma("unroll") for (int n = 0; n < 2; ++n) _Pragma("unroll") for (int k = 0; k < 2; ++k) \
;         acc[ai][bj][m][n] = __builtin_amdgcn_mfma_f32_16x16x32_bf16(Bt[n][k], At[m][k], acc[ai][bj][m][n], 0, 0, 0); __builtin_amdgcn_s_setprio(0); } while (0)
; #define PG8_WAIT_V(n) asm volatile("s_waitcnt vmcnt(" #n ")" ::: "memory")
; #define PG8_WAIT_L(n) asm volatile("s_waitcnt lgkmcnt(" #n ")" ::: "memory")
; #define PG8_BAR __builtin_amdgcn_s_barrier()
; #define PG8_SCHED __builtin_amdgcn_sched_barrier(0)
; template <class Epi, class Sched, bool ALIGN_EPI = false, bool SP2 = false>
; __device__ __forceinline__ void gemm_phase(PG8_LAS unsigned char* lds, const Gemm g, const Sched& S, const Epi& E) {
;     ...
;             PG8_WAIT_V(8); PG8_WAIT_L(0); PG8_BAR; PG8_MMA(1, 0, At, B0); PG8_MMA(1, 1, At, B1); PG8_BAR; PG8_SCHED;
;             PG8_LDB(B0, 1, 0); PG8_LDB(B1, 1, 1); PG8_SCHED; PG8_LDA(At, 1, 0); PG8_STAGE(PG8_SA(0, 1), a2 + hstep, voffA);
;             PG8_WAIT_V(8); PG8_WAIT_L(0); PG8_BAR; PG8_MMA(0, 0, At, B0); PG8_MMA(0, 1, At, B1); PG8_BAR; PG8_SCHED;
	v_mfma_f32_16x16x32_bf16 v[62:65], v[156:159], v[188:191], 0
	v_mfma_f32_16x16x32_bf16 v[58:61], v[164:167], v[188:191], 0
	v_mfma_f32_16x16x32_bf16 v[46:49], v[156:159], v[196:199], 0
	v_mfma_f32_16x16x32_bf16 v[42:45], v[164:167], v[196:199], 0
	v_mfma_f32_16x16x32_bf16 v[34:37], v[156:159], v[204:207], 0
	v_mfma_f32_16x16x32_bf16 v[26:29], v[164:167], v[204:207], 0
	v_mfma_f32_16x16x32_bf16 v[18:21], v[156:159], v[212:215], 0
	v_mfma_f32_16x16x32_bf16 v[10:13], v[164:167], v[212:215], 0
	v_mfma_f32_16x16x32_bf16 v[62:65], v[160:163], v[192:195], v[62:65]
	v_mfma_f32_16x16x32_bf16 v[58:61], v[168:171], v[192:195], v[58:61]
	v_mfma_f32_16x16x32_bf16 v[46:49], v[160:163], v[200:203], v[46:49]
	v_mfma_f32_16x16x32_bf16 v[42:45], v[168:171], v[200:203], v[42:45]
	v_mfma_f32_16x16x32_bf16 v[34:37], v[160:163], v[208:211], v[34:37]
	v_mfma_f32_16x16x32_bf16 v[26:29], v[168:171], v[208:211], v[26:29]
	v_mfma_f32_16x16x32_bf16 v[18:21], v[160:163], v[220:223], v[18:21]
	v_mfma_f32_16x16x32_bf16 v[10:13], v[168:171], v[220:223], v[10:13]
	s_setprio 0
	s_setprio 1
	v_mfma_f32_16x16x32_bf16 v[54:57], v[172:175], v[188:191], 0
	v_mfma_f32_16x16x32_bf16 v[50:53], v[180:183], v[188:191], 0
	v_mfma_f32_16x16x32_bf16 v[38:41], v[172:175], v[196:199], 0
	v_mfma_f32_16x16x32_bf16 v[30:33], v[180:183], v[196:199], 0
	v_mfma_f32_16x16x32_bf16 v[22:25], v[172:175], v[204:207], 0
	v_mfma_f32_16x16x32_bf16 v[14:17], v[180:183], v[204:207], 0
	v_mfma_f32_16x16x32_bf16 v[6:9], v[172:175], v[212:215], 0
	v_mfma_f32_16x16x32_bf16 v[2:5], v[180:183], v[212:215], 0
	v_mfma_f32_16x16x32_bf16 v[54:57], v[176:179], v[192:195], v[54:57]
	v_mfma_f32_16x16x32_bf16 v[50:53], v[184:187], v[192:195], v[50:53]
	v_mfma_f32_16x16x32_bf16 v[38:41], v[176:179], v[200:203], v[38:41]
	v_mfma_f32_16x16x32_bf16 v[30:33], v[184:187], v[200:203], v[30:33]
	v_mfma_f32_16x16x32_bf16 v[22:25], v[176:179], v[208:211], v[22:25]
	v_mfma_f32_16x16x32_bf16 v[14:17], v[184:187], v[208:211], v[14:17]
	v_mfma_f32_16x16x32_bf16 v[6:9], v[176:179], v[220:223], v[6:9]
	v_mfma_f32_16x16x32_bf16 v[2:5], v[184:187], v[220:223], v[2:5]
	s_barrier
	s_setprio 0
	s_add_i32 s76, 0, 0x18000
	v_add_u32_e32 v148, s76, v149
	s_add_i32 s77, 0, 0x1c000
	ds_read_b128 v[156:159], v148
	ds_read_b128 v[160:163], v148 offset:1024
	ds_read_b128 v[164:167], v148 offset:2048
	ds_read_b128 v[168:171], v148 offset:3072
	v_add_u32_e32 v148, s77, v149
	ds_read_b128 v[172:175], v148
	ds_read_b128 v[176:179], v148 offset:1024
	ds_read_b128 v[180:183], v148 offset:2048
	ds_read_b128 v[184:187], v148 offset:3072
	s_add_u32 s40, s40, 0x4000
	s_addc_u32 s41, s41, 0
	s_mov_b32 m0, s50
	ds_read_b128 v[188:191], v152 offset:32768
	ds_read_b128 v[192:195], v152 offset:33792
	ds_read_b128 v[196:199], v152 offset:34816
	ds_read_b128 v[200:203], v152 offset:35840
	ds_read_b128 v[204:207], v152 offset:36864
	ds_read_b128 v[208:211], v152 offset:37888
	ds_read_b128 v[212:215], v152 offset:38912
	ds_read_b128 v[220:223], v152 offset:39936
	global_load_lds_dwordx4 v136, s[40:41]
	s_mov_b32 m0, s51
	s_nop 0
	global_load_lds_dwordx4 v132, s[40:41]
	s_waitcnt vmcnt(8)
	s_waitcnt lgkmcnt(0)
	s_setprio 1
	s_barrier
	v_mfma_f32_16x16x32_bf16 v[126:129], v[156:159], v[188:191], v[126:129]
	v_mfma_f32_16x16x32_bf16 v[122:125], v[164:167], v[188:191], v[122:125]
	v_mfma_f32_16x16x32_bf16 v[114:117], v[156:159], v[196:199], v[114:117]
	v_mfma_f32_16x16x32_bf16 v[106:109], v[164:167], v[196:199], v[106:109]
	v_mfma_f32_16x16x32_bf16 v[98:101], v[156:159], v[204:207], v[98:101]
	v_mfma_f32_16x16x32_bf16 v[90:93], v[164:167], v[204:207], v[90:93]
	v_mfma_f32_16x16x32_bf16 v[78:81], v[156:159], v[212:215], v[78:81]
	v_mfma_f32_16x16x32_bf16 v[74:77], v[164:167], v[212:215], v[74:77]
	v_mfma_f32_16x16x32_bf16 v[126:129], v[160:163], v[192:195], v[126:129]
	v_mfma_f32_16x16x32_bf16 v[122:125], v[168:171], v[192:195], v[122:125]
	v_mfma_f32_16x16x32_bf16 v[114:117], v[160:163], v[200:203], v[114:117]
	v_mfma_f32_16x16x32_bf16 v[106:109], v[168:171], v[200:203], v[106:109]
	v_mfma_f32_16x16x32_bf16 v[98:101], v[160:163], v[208:211], v[98:101]
	v_mfma_f32_16x16x32_bf16 v[90:93], v[168:171], v[208:211], v[90:93]
	v_mfma_f32_16x16x32_bf16 v[78:81], v[160:163], v[220:223], v[78:81]
	v_mfma_f32_16x16x32_bf16 v[74:77], v[168:171], v[220:223], v[74:77]
	s_setprio 0
	s_setprio 1
	v_mfma_f32_16x16x32_bf16 v[118:121], v[172:175], v[188:191], v[118:121]
	v_mfma_f32_16x16x32_bf16 v[110:113], v[180:183], v[188:191], v[110:113]
	v_mfma_f32_16x16x32_bf16 v[102:105], v[172:175], v[196:199], v[102:105]
	v_mfma_f32_16x16x32_bf16 v[94:97], v[180:183], v[196:199], v[94:97]
	v_mfma_f32_16x16x32_bf16 v[86:89], v[172:175], v[204:207], v[86:89]
	v_mfma_f32_16x16x32_bf16 v[82:85], v[180:183], v[204:207], v[82:85]
	v_mfma_f32_16x16x32_bf16 v[70:73], v[172:175], v[212:215], v[70:73]
	v_mfma_f32_16x16x32_bf16 v[66:69], v[180:183], v[212:215], v[66:69]
	v_mfma_f32_16x16x32_bf16 v[118:121], v[176:179], v[192:195], v[118:121]
	v_mfma_f32_16x16x32_bf16 v[110:113], v[184:187], v[192:195], v[110:113]
	v_mfma_f32_16x16x32_bf16 v[102:105], v[176:179], v[200:203], v[102:105]
	v_mfma_f32_16x16x32_bf16 v[94:97], v[184:187], v[200:203], v[94:97]
	v_mfma_f32_16x16x32_bf16 v[86:89], v[176:179], v[208:211], v[86:89]
	v_mfma_f32_16x16x32_bf16 v[82:85], v[184:187], v[208:211], v[82:85]
	v_mfma_f32_16x16x32_bf16 v[70:73], v[176:179], v[220:223], v[70:73]
	v_mfma_f32_16x16x32_bf16 v[66:69], v[184:187], v[220:223], v[66:69]
	s_barrier
; #define PG8_STAGE(bufoff, gbase, voff) do { _Pragma("unroll") for (int _i = 0; _i < 2; ++_i) \
;         __builtin_amdgcn_global_load_lds((const unsigned*)((const char*)(gbase) + (voff)[_i]), (PG8_LAS unsigned*)(lds + (bufoff) + ldsw + _i * 8192), 16, 0, 0); } while (0)
; #define PG8_LDA(dst, b, h) do { _Pragma("unroll") for (int m = 0; m < 4; ++m) _Pragma("unroll") for (int k = 0; k < 2; ++k) dst[m][k] = *(const PG8_LAS bf16x8*)(lds + PG8_SA(b, h) + aoff + m * 2048 + k * 1024); } while (0)
; #define PG8_MMA(ai, bj, At, Bt) do { __builtin_amdgcn_s_setprio(1); _Pragma("unroll") for (int m = 0; m < 4; ++m) _Pragma("unroll") for (int n = 0; n < 2; ++n) _Pragma("unroll") for (int k = 0; k < 2; ++k) \
;         acc[ai][bj][m][n] = __builtin_amdgcn_mfma_f32_16x16x32_bf16(Bt[n][k], At[m][k], acc[ai][bj][m][n], 0, 0, 0); __builtin_amdgcn_s_setprio(0); } while (0)
; #define PG8_WAIT_V(n) asm volatile("s_waitcnt vmcnt(" #n ")" ::: "memory")
; #define PG8_WAIT_L(n) asm volatile("s_waitcnt lgkmcnt(" #n ")" ::: "memory")
; #define PG8_BAR __builtin_amdgcn_s_barrier()
; #define PG8_SCHED __builtin_amdgcn_sched_barrier(0)
; template <class Epi, class Sched, bool ALIGN_EPI = false, bool SP2 = false>
; __device__ __forceinline__ void gemm_phase(PG8_LAS unsigned char* lds, const Gemm g, const Sched& S, const Epi& E) {
;     ...
;             PG8_LDA(At, 1, 1); PG8_STAGE(PG8_SB(1, 0), b3, voffB); PG8_STAGE(PG8_SB(1, 1), b3 + hstepB, voffB); PG8_STAGE(PG8_SA(1, 0), a3, voffA);
;             PG8_WAIT_V(8); PG8_WAIT_L(0); PG8_BAR; PG8_MMA(1, 0, At, B0); PG8_MMA(1, 1, At, B1); PG8_BAR; PG8_SCHED;
	s_setprio 0
	s_add_u32 s40, s28, 0x8000
	s_addc_u32 s41, s29, 0
	s_add_i32 s76, s76, s0
	s_mov_b32 m0, s76
	ds_read_b128 v[188:191], v152 offset:49152
	ds_read_b128 v[192:195], v152 offset:50176
	ds_read_b128 v[196:199], v152 offset:51200
	ds_read_b128 v[200:203], v152 offset:52224
	ds_read_b128 v[204:207], v152 offset:53248
	ds_read_b128 v[208:211], v152 offset:54272
	ds_read_b128 v[212:215], v152 offset:55296
	ds_read_b128 v[220:223], v152 offset:56320
	global_load_lds_dwordx4 v134, s[40:41]
	s_add_i32 m0, s76, 0x2000
	s_add_u32 s28, s28, 0x9000
	v_lshl_add_u64 v[216:217], s[40:41], 0, v[130:131]
	s_addc_u32 s29, s29, 0
	s_add_i32 s40, s77, s0
	global_load_lds_dwordx4 v[216:217], off
	s_mov_b32 m0, s40
	s_nop 0
	global_load_lds_dwordx4 v134, s[28:29]
	s_add_i32 m0, s40, 0x2000
	s_nop 0
	global_load_lds_dwordx4 v130, s[28:29]
	s_mov_b32 m0, s54
	s_nop 0
	global_load_lds_dwordx4 v136, s[26:27]
	s_mov_b32 m0, s55
	s_nop 0
	global_load_lds_dwordx4 v132, s[26:27]
	s_waitcnt vmcnt(8)
	s_waitcnt lgkmcnt(0)
	s_setprio 1
	s_barrier
	v_mfma_f32_16x16x32_bf16 v[62:65], v[156:159], v[188:191], v[62:65]
	v_mfma_f32_16x16x32_bf16 v[58:61], v[164:167], v[188:191], v[58:61]
	v_mfma_f32_16x16x32_bf16 v[46:49], v[156:159], v[196:199], v[46:49]
	v_mfma_f32_16x16x32_bf16 v[42:45], v[164:167], v[196:199], v[42:45]
	v_mfma_f32_16x16x32_bf16 v[34:37], v[156:159], v[204:207], v[34:37]
	v_mfma_f32_16x16x32_bf16 v[26:29], v[164:167], v[204:207], v[26:29]
	v_mfma_f32_16x16x32_bf16 v[18:21], v[156:159], v[212:215], v[18:21]
	v_mfma_f32_16x16x32_bf16 v[10:13], v[164:167], v[212:215], v[10:13]
	v_mfma_f32_16x16x32_bf16 v[62:65], v[160:163], v[192:195], v[62:65]
	v_mfma_f32_16x16x32_bf16 v[58:61], v[168:171], v[192:195], v[58:61]
	v_mfma_f32_16x16x32_bf16 v[46:49], v[160:163], v[200:203], v[46:49]
	v_mfma_f32_16x16x32_bf16 v[42:45], v[168:171], v[200:203], v[42:45]
	v_mfma_f32_16x16x32_bf16 v[34:37], v[160:163], v[208:211], v[34:37]
	v_mfma_f32_16x16x32_bf16 v[26:29], v[168:171], v[208:211], v[26:29]
	v_mfma_f32_16x16x32_bf16 v[18:21], v[160:163], v[220:223], v[18:21]
	v_mfma_f32_16x16x32_bf16 v[10:13], v[168:171], v[220:223], v[10:13]
	s_setprio 0
	s_setprio 1
	v_mfma_f32_16x16x32_bf16 v[54:57], v[172:175], v[188:191], v[54:57]
	v_mfma_f32_16x16x32_bf16 v[50:53], v[180:183], v[188:191], v[50:53]
	v_mfma_f32_16x16x32_bf16 v[38:41], v[172:175], v[196:199], v[38:41]
	v_mfma_f32_16x16x32_bf16 v[30:33], v[180:183], v[196:199], v[30:33]
	v_mfma_f32_16x16x32_bf16 v[22:25], v[172:175], v[204:207], v[22:25]
	v_mfma_f32_16x16x32_bf16 v[14:17], v[180:183], v[204:207], v[14:17]
	v_mfma_f32_16x16x32_bf16 v[6:9], v[172:175], v[212:215], v[6:9]
	v_mfma_f32_16x16x32_bf16 v[2:5], v[180:183], v[212:215], v[2:5]
	v_mfma_f32_16x16x32_bf16 v[54:57], v[176:179], v[192:195], v[54:57]
	v_mfma_f32_16x16x32_bf16 v[50:53], v[184:187], v[192:195], v[50:53]
	v_mfma_f32_16x16x32_bf16 v[38:41], v[176:179], v[200:203], v[38:41]
	v_mfma_f32_16x16x32_bf16 v[30:33], v[184:187], v[200:203], v[30:33]
	v_mfma_f32_16x16x32_bf16 v[22:25], v[176:179], v[208:211], v[22:25]
	v_mfma_f32_16x16x32_bf16 v[14:17], v[184:187], v[208:211], v[14:17]
	v_mfma_f32_16x16x32_bf16 v[6:9], v[176:179], v[220:223], v[6:9]
	v_mfma_f32_16x16x32_bf16 v[2:5], v[184:187], v[220:223], v[2:5]
	s_barrier
	s_setprio 0
	s_add_i32 s75, s75, 2
	s_add_u32 s24, s24, 0x10000
	s_addc_u32 s25, s25, 0
	s_add_u32 s73, s73, 0x10000
	s_addc_u32 s74, s74, 0
	.p2align 6

; template <class Epi, class Sched, bool ALIGN_EPI = false, bool SP2 = false>
; __device__ __forceinline__ void gemm_phase(PG8_LAS unsigned char* lds, const Gemm g, const Sched& S, const Epi& E) {
;     ...
;         const bool has_next = S.next(ui + 1, nxt);
;         const char* nA = has_next ? (const char*)g.A + (size_t)nxt.pm * tstep : cA; const char* nB = has_next ? (const char*)g.Bt + (size_t)nxt.pn * tstep : cB;
;     ...
; #pragma unroll
;         for (int a = 0; a < 2; ++a)
; #pragma unroll
;             for (int b = 0; b < 2; ++b)
; #pragma unroll
;                 for (int m = 0; m < 4; ++m)
; #pragma unroll
;                     for (int n = 0; n < 2; ++n) acc[a][b][m][n] = (f32x4){0.f, 0.f, 0.f, 0.f};
;         cur = nxt; cA = nA; cB = nB; ++ui;
.LBB0_379:
	s_ashr_i32 s21, s20, 31
	s_lshl_b64 s[0:1], s[20:21], 19
	s_add_u32 s22, s40, s0
	s_addc_u32 s23, s41, s1
	s_and_b64 s[0:1], s[4:5], exec
	s_cselect_b32 s0, s23, s29
	s_cselect_b32 s1, s22, s28
	s_ashr_i32 s19, s18, 31
	s_lshl_b64 s[24:25], s[18:19], 19
	s_add_u32 s24, s68, s24
	s_addc_u32 s25, s69, s25
	s_and_b64 s[44:45], s[4:5], exec
	s_cselect_b32 s19, s25, s47
	s_cselect_b32 s21, s24, s46
	s_lshl_b32 s27, s27, 2
	s_or_b32 s44, s27, s80
	v_mov_b32_e32 v4, v2
	v_mov_b32_e32 v5, v2
	s_add_u32 s27, s46, 0x10000
	v_mov_b32_e32 v3, v2
	v_mov_b64_e32 v[8:9], v[4:5]
	v_mov_b64_e32 v[12:13], v[4:5]
	v_mov_b64_e32 v[24:25], v[4:5]
	v_mov_b64_e32 v[28:29], v[4:5]
	v_mov_b64_e32 v[40:41], v[4:5]
	v_mov_b64_e32 v[44:45], v[4:5]
	v_mov_b64_e32 v[56:57], v[4:5]
	v_mov_b64_e32 v[60:61], v[4:5]
	v_mov_b64_e32 v[16:17], v[4:5]
	v_mov_b64_e32 v[20:21], v[4:5]
	v_mov_b64_e32 v[32:33], v[4:5]
	v_mov_b64_e32 v[36:37], v[4:5]
	v_mov_b64_e32 v[48:49], v[4:5]
	v_mov_b64_e32 v[52:53], v[4:5]
	v_mov_b64_e32 v[64:65], v[4:5]
	v_mov_b64_e32 v[68:69], v[4:5]
	v_mov_b64_e32 v[72:73], v[4:5]
	v_mov_b64_e32 v[76:77], v[4:5]
	v_mov_b64_e32 v[88:89], v[4:5]
	v_mov_b64_e32 v[92:93], v[4:5]
	v_mov_b64_e32 v[104:105], v[4:5]
	v_mov_b64_e32 v[108:109], v[4:5]
	v_mov_b64_e32 v[120:121], v[4:5]
	v_mov_b64_e32 v[124:125], v[4:5]
	v_mov_b64_e32 v[80:81], v[4:5]
	v_mov_b64_e32 v[84:85], v[4:5]
	v_mov_b64_e32 v[96:97], v[4:5]
	v_mov_b64_e32 v[100:101], v[4:5]
	v_mov_b64_e32 v[112:113], v[4:5]
	v_mov_b64_e32 v[116:117], v[4:5]
	v_mov_b64_e32 v[128:129], v[4:5]
	v_mov_b64_e32 v[132:133], v[4:5]
	v_lshl_add_u64 v[182:183], s[28:29], 0, v[210:211]
	v_lshl_add_u64 v[184:185], s[28:29], 0, v[212:213]
	s_addc_u32 s45, s47, 0
	s_mov_b32 s56, -2
	s_mov_b64 s[46:47], 0
	v_mov_b64_e32 v[6:7], v[2:3]
	v_mov_b64_e32 v[10:11], v[2:3]
	v_mov_b64_e32 v[22:23], v[2:3]
	v_mov_b64_e32 v[26:27], v[2:3]
	v_mov_b64_e32 v[38:39], v[2:3]
	v_mov_b64_e32 v[42:43], v[2:3]
	v_mov_b64_e32 v[54:55], v[2:3]
	v_mov_b64_e32 v[58:59], v[2:3]
	v_mov_b64_e32 v[14:15], v[2:3]
	v_mov_b64_e32 v[18:19], v[2:3]
	v_mov_b64_e32 v[30:31], v[2:3]
	v_mov_b64_e32 v[34:35], v[2:3]
	v_mov_b64_e32 v[46:47], v[2:3]
	v_mov_b64_e32 v[50:51], v[2:3]
	v_mov_b64_e32 v[62:63], v[2:3]
	v_mov_b64_e32 v[66:67], v[2:3]
	v_mov_b64_e32 v[70:71], v[2:3]
	v_mov_b64_e32 v[74:75], v[2:3]
	v_mov_b64_e32 v[86:87], v[2:3]
	v_mov_b64_e32 v[90:91], v[2:3]
	v_mov_b64_e32 v[102:103], v[2:3]
	v_mov_b64_e32 v[106:107], v[2:3]
	v_mov_b64_e32 v[118:119], v[2:3]
	v_mov_b64_e32 v[122:123], v[2:3]
	v_mov_b64_e32 v[78:79], v[2:3]
	v_mov_b64_e32 v[82:83], v[2:3]
	v_mov_b64_e32 v[94:95], v[2:3]
	v_mov_b64_e32 v[98:99], v[2:3]
	v_mov_b64_e32 v[110:111], v[2:3]
	v_mov_b64_e32 v[114:115], v[2:3]
	v_mov_b64_e32 v[126:127], v[2:3]
	v_mov_b64_e32 v[130:131], v[2:3]
	s_branch .LBB0_381
	.p2align 6

; #define PG8_STAGE(bufoff, gbase, voff) do { _Pragma("unroll") for (int _i = 0; _i < 2; ++_i) \
;         __builtin_amdgcn_global_load_lds((const unsigned*)((const char*)(gbase) + (voff)[_i]), (PG8_LAS unsigned*)(lds + (bufoff) + ldsw + _i * 8192), 16, 0, 0); } while (0)
; #define PG8_LDA(dst, b, h) do { _Pragma("unroll") for (int m = 0; m < 4; ++m) _Pragma("unroll") for (int k = 0; k < 2; ++k) dst[m][k] = *(const PG8_LAS bf16x8*)(lds + PG8_SA(b, h) + aoff + m * 2048 + k * 1024); } while (0)
; #define PG8_LDB(dst, b, h) do { _Pragma("unroll") for (int n = 0; n < 2; ++n) _Pragma("unroll") for (int k = 0; k < 2; ++k) dst[n][k] = *(const PG8_LAS bf16x8*)(lds + PG8_SB(b, h) + boff + n * 2048 + k * 1024); } while (0)
; #define PG8_WAIT_V(n) asm volatile("s_waitcnt vmcnt(" #n ")" ::: "memory")
; #define PG8_WAIT_L(n) asm volatile("s_waitcnt lgkmcnt(" #n ")" ::: "memory")
; #define PG8_BAR __builtin_amdgcn_s_barrier()
; template <class Epi, class Sched, bool ALIGN_EPI = false, bool SP2 = false>
; __device__ __forceinline__ void gemm_phase(PG8_LAS unsigned char* lds, const Gemm g, const Sched& S, const Epi& E) {
;     ...
;         const bool has_next = S.next(ui + 1, nxt);
;         const char* nA = has_next ? (const char*)g.A + (size_t)nxt.pm * tstep : cA; const char* nB = has_next ? (const char*)g.Bt + (size_t)nxt.pn * tstep : cB;
;         for (int t = 0; t < nt; t += 2) {
;             if constexpr (Epi::HAS_MID) { if (t == (nt >> 1)) E.mid(acc, cur, wr, wc, fr, fq); }
;             const bool last = (t == nt - 2);
;             const char* a1 = cA + (size_t)(t + 1) * kstep;
;             const char* a2 = last ? nA : cA + (size_t)(t + 2) * kstep; const char* b2 = last ? nB : cB + (size_t)(t + 2) * kstep;
;             const char* a3 = a2 + kstep; const char* b3 = b2 + kstep;
;             if (last && has_next) S.a_ready(nxt);
;             if constexpr (SP2) {
;             PG8_LDB(B0, 0, 0); PG8_LDB(B1, 0, 1); PG8_SCHED; PG8_LDA(At, 0, 0); PG8_STAGE(PG8_SA(1, 1), a1 + hstep, voffA);
;             PG8_WAIT_V(8); PG8_WAIT_L(0); PG8_BAR; PG8_MMA(0, 0, At, B0); PG8_MMA(0, 1, At, B1); PG8_BAR; PG8_SCHED;
;             PG8_LDA(At, 0, 1); PG8_STAGE(PG8_SB(0, 0), b2, voffB); PG8_STAGE(PG8_SB(0, 1), b2 + hstepB, voffB); PG8_STAGE(PG8_SA(0, 0), a2, voffA);
;             PG8_WAIT_V(8); PG8_WAIT_L(0); PG8_BAR; PG8_MMA(1, 0, At, B0); PG8_MMA(1, 1, At, B1); PG8_BAR; PG8_SCHED;
.LBB0_476:
	s_ashr_i32 s29, s28, 31
	s_lshl_b64 s[42:43], s[28:29], 19
	s_add_u32 s42, s3, s42
	s_addc_u32 s43, s76, s43
	s_and_b64 s[44:45], s[4:5], exec
	s_cselect_b32 s29, s43, s51
	s_cselect_b32 s47, s42, s50
	s_ashr_i32 s27, s26, 31
	s_lshl_b64 s[44:45], s[26:27], 19
	s_add_u32 s44, s66, s44
	s_addc_u32 s45, s67, s45
	s_and_b64 s[52:53], s[4:5], exec
	s_cselect_b32 s27, s45, s69
	s_cselect_b32 s52, s44, s68
	s_add_u32 s50, s50, 0xc000
	s_addc_u32 s51, s51, 0
	s_add_u32 s53, s68, 0x10000
	s_addc_u32 s54, s69, 0
	s_mov_b32 s55, -2
	s_waitcnt lgkmcnt(0)
	ds_read_b128 v[130:133], v201
	ds_read_b128 v[134:137], v201 offset:1024
	ds_read_b128 v[138:141], v201 offset:2048
	ds_read_b128 v[142:145], v201 offset:3072
	ds_read_b128 v[146:149], v202
	ds_read_b128 v[150:153], v202 offset:1024
	ds_read_b128 v[154:157], v202 offset:2048
	ds_read_b128 v[158:161], v202 offset:3072
	s_add_u32 s68, s50, 0x4000
	s_addc_u32 s69, s51, 0
	s_cmp_eq_u32 s55, 12
	s_cselect_b32 s72, s47, s68
	s_cselect_b32 s73, s29, s69
	s_cselect_b32 s70, s52, s53
	s_cselect_b32 s71, s27, s54
	s_add_u32 s68, s72, 0x8000
	s_addc_u32 s69, s73, 0
	s_add_i32 m0, s1, 0xc000
	ds_read_b128 v[162:165], v203
	ds_read_b128 v[166:169], v203 offset:1024
	ds_read_b128 v[170:173], v203 offset:2048
	ds_read_b128 v[174:177], v203 offset:3072
	ds_read_b128 v[208:211], v203 offset:4096
	ds_read_b128 v[212:215], v203 offset:5120
	ds_read_b128 v[220:223], v203 offset:6144
	ds_read_b128 v[224:227], v203 offset:7168
	global_load_lds_dwordx4 v188, s[50:51]
	s_add_i32 m0, s1, 0xe000
	s_nop 0
	global_load_lds_dwordx4 v190, s[50:51]
	s_waitcnt vmcnt(8)
	s_waitcnt lgkmcnt(0)
	s_setprio 1
	s_barrier
	v_mfma_f32_16x16x32_bf16 v[126:129], v[130:133], v[162:165], 0
	v_mfma_f32_16x16x32_bf16 v[122:125], v[138:141], v[162:165], 0
	v_mfma_f32_16x16x32_bf16 v[110:113], v[130:133], v[170:173], 0
	v_mfma_f32_16x16x32_bf16 v[106:109], v[138:141], v[170:173], 0
	v_mfma_f32_16x16x32_bf16 v[94:97], v[130:133], v[208:211], 0
	v_mfma_f32_16x16x32_bf16 v[90:93], v[138:141], v[208:211], 0
	v_mfma_f32_16x16x32_bf16 v[78:81], v[130:133], v[220:223], 0
	v_mfma_f32_16x16x32_bf16 v[74:77], v[138:141], v[220:223], 0
	v_mfma_f32_16x16x32_bf16 v[126:129], v[134:137], v[166:169], v[126:129]
	v_mfma_f32_16x16x32_bf16 v[122:125], v[142:145], v[166:169], v[122:125]
	v_mfma_f32_16x16x32_bf16 v[110:113], v[134:137], v[174:177], v[110:113]
	v_mfma_f32_16x16x32_bf16 v[106:109], v[142:145], v[174:177], v[106:109]
	v_mfma_f32_16x16x32_bf16 v[94:97], v[134:137], v[212:215], v[94:97]
	v_mfma_f32_16x16x32_bf16 v[90:93], v[142:145], v[212:215], v[90:93]
	v_mfma_f32_16x16x32_bf16 v[78:81], v[134:137], v[224:227], v[78:81]
	v_mfma_f32_16x16x32_bf16 v[74:77], v[142:145], v[224:227], v[74:77]
	s_setprio 0
	s_setprio 1
	v_mfma_f32_16x16x32_bf16 v[118:121], v[146:149], v[162:165], 0
	v_mfma_f32_16x16x32_bf16 v[114:117], v[154:157], v[162:165], 0
	v_mfma_f32_16x16x32_bf16 v[102:105], v[146:149], v[170:173], 0
	v_mfma_f32_16x16x32_bf16 v[98:101], v[154:157], v[170:173], 0
	v_mfma_f32_16x16x32_bf16 v[86:89], v[146:149], v[208:211], 0
	v_mfma_f32_16x16x32_bf16 v[82:85], v[154:157], v[208:211], 0
	v_mfma_f32_16x16x32_bf16 v[70:73], v[146:149], v[220:223], 0
	v_mfma_f32_16x16x32_bf16 v[66:69], v[154:157], v[220:223], 0
	v_mfma_f32_16x16x32_bf16 v[118:121], v[150:153], v[166:169], v[118:121]
	v_mfma_f32_16x16x32_bf16 v[114:117], v[158:161], v[166:169], v[114:117]
	v_mfma_f32_16x16x32_bf16 v[102:105], v[150:153], v[174:177], v[102:105]
	v_mfma_f32_16x16x32_bf16 v[98:101], v[158:161], v[174:177], v[98:101]
	v_mfma_f32_16x16x32_bf16 v[86:89], v[150:153], v[212:215], v[86:89]
	v_mfma_f32_16x16x32_bf16 v[82:85], v[158:161], v[212:215], v[82:85]
	v_mfma_f32_16x16x32_bf16 v[70:73], v[150:153], v[224:227], v[70:73]
	v_mfma_f32_16x16x32_bf16 v[66:69], v[158:161], v[224:227], v[66:69]
	s_barrier
	s_setprio 0
	s_add_i32 s79, s77, s0
	s_mov_b32 m0, s79
	ds_read_b128 v[162:165], v203 offset:16384
	ds_read_b128 v[166:169], v203 offset:17408
	ds_read_b128 v[170:173], v203 offset:18432
	ds_read_b128 v[174:177], v203 offset:19456
	ds_read_b128 v[208:211], v203 offset:20480
	ds_read_b128 v[212:215], v203 offset:21504
	ds_read_b128 v[220:223], v203 offset:22528
	ds_read_b128 v[224:227], v203 offset:23552
	global_load_lds_dwordx4 v180, s[70:71]
	s_add_i32 m0, s79, 0x2000
	s_add_u32 s80, s70, 0x1000
	s_addc_u32 s81, s71, 0
	s_add_i32 s79, s78, s0
	global_load_lds_dwordx4 v184, s[70:71]
	s_mov_b32 m0, s79
	s_nop 0
	global_load_lds_dwordx4 v180, s[80:81]
	s_add_i32 m0, s79, 0x2000
	s_nop 0
	global_load_lds_dwordx4 v184, s[80:81]
	s_mov_b32 m0, s1
	s_nop 0
	global_load_lds_dwordx4 v178, s[72:73]
	s_mov_b32 m0, s49
	s_nop 0
	global_load_lds_dwordx4 v182, s[72:73]
	s_waitcnt vmcnt(8)
	s_waitcnt lgkmcnt(0)
	s_setprio 1
	s_barrier
; #define PG8_STAGE(bufoff, gbase, voff) do { _Pragma("unroll") for (int _i = 0; _i < 2; ++_i) \
;         __builtin_amdgcn_global_load_lds((const unsigned*)((const char*)(gbase) + (voff)[_i]), (PG8_LAS unsigned*)(lds + (bufoff) + ldsw + _i * 8192), 16, 0, 0); } while (0)
; #define PG8_LDA(dst, b, h) do { _Pragma("unroll") for (int m = 0; m < 4; ++m) _Pragma("unroll") for (int k = 0; k < 2; ++k) dst[m][k] = *(const PG8_LAS bf16x8*)(lds + PG8_SA(b, h) + aoff + m * 2048 + k * 1024); } while (0)
; #define PG8_LDB(dst, b, h) do { _Pragma("unroll") for (int n = 0; n < 2; ++n) _Pragma("unroll") for (int k = 0; k < 2; ++k) dst[n][k] = *(const PG8_LAS bf16x8*)(lds + PG8_SB(b, h) + boff + n * 2048 + k * 1024); } while (0)
; #define PG8_MMA(ai, bj, At, Bt) do { __builtin_amdgcn_s_setprio(1); _Pragma("unroll") for (int m = 0; m < 4; ++m) _Pragma("unroll") for (int n = 0; n < 2; ++n) _Pragma("unroll") for (int k = 0; k < 2; ++k) \
;         acc[ai][bj][m][n] = __builtin_amdgcn_mfma_f32_16x16x32_bf16(Bt[n][k], At[m][k], acc[ai][bj][m][n], 0, 0, 0); __builtin_amdgcn_s_setprio(0); } while (0)
; #define PG8_WAIT_V(n) asm volatile("s_waitcnt vmcnt(" #n ")" ::: "memory")
; #define PG8_WAIT_L(n) asm volatile("s_waitcnt lgkmcnt(" #n ")" ::: "memory")
; #define PG8_BAR __builtin_amdgcn_s_barrier()
; #define PG8_SCHED __builtin_amdgcn_sched_barrier(0)
; template <class Epi, class Sched, bool ALIGN_EPI = false, bool SP2 = false>
; __device__ __forceinline__ void gemm_phase(PG8_LAS unsigned char* lds, const Gemm g, const Sched& S, const Epi& E) {
;     ...
;             PG8_WAIT_V(8); PG8_WAIT_L(0); PG8_BAR; PG8_MMA(1, 0, At, B0); PG8_MMA(1, 1, At, B1); PG8_BAR; PG8_SCHED;
;             PG8_LDB(B0, 1, 0); PG8_LDB(B1, 1, 1); PG8_SCHED; PG8_LDA(At, 1, 0); PG8_STAGE(PG8_SA(0, 1), a2 + hstep, voffA);
;             PG8_WAIT_V(8); PG8_WAIT_L(0); PG8_BAR; PG8_MMA(0, 0, At, B0); PG8_MMA(0, 1, At, B1); PG8_BAR; PG8_SCHED;
	v_mfma_f32_16x16x32_bf16 v[62:65], v[130:133], v[162:165], 0
	v_mfma_f32_16x16x32_bf16 v[58:61], v[138:141], v[162:165], 0
	v_mfma_f32_16x16x32_bf16 v[46:49], v[130:133], v[170:173], 0
	v_mfma_f32_16x16x32_bf16 v[42:45], v[138:141], v[170:173], 0
	v_mfma_f32_16x16x32_bf16 v[30:33], v[130:133], v[208:211], 0
	v_mfma_f32_16x16x32_bf16 v[26:29], v[138:141], v[208:211], 0
	v_mfma_f32_16x16x32_bf16 v[14:17], v[130:133], v[220:223], 0
	v_mfma_f32_16x16x32_bf16 v[10:13], v[138:141], v[220:223], 0
	v_mfma_f32_16x16x32_bf16 v[62:65], v[134:137], v[166:169], v[62:65]
	v_mfma_f32_16x16x32_bf16 v[58:61], v[142:145], v[166:169], v[58:61]
	v_mfma_f32_16x16x32_bf16 v[46:49], v[134:137], v[174:177], v[46:49]
	v_mfma_f32_16x16x32_bf16 v[42:45], v[142:145], v[174:177], v[42:45]
	v_mfma_f32_16x16x32_bf16 v[30:33], v[134:137], v[212:215], v[30:33]
	v_mfma_f32_16x16x32_bf16 v[26:29], v[142:145], v[212:215], v[26:29]
	v_mfma_f32_16x16x32_bf16 v[14:17], v[134:137], v[224:227], v[14:17]
	v_mfma_f32_16x16x32_bf16 v[10:13], v[142:145], v[224:227], v[10:13]
	s_setprio 0
	s_setprio 1
	v_mfma_f32_16x16x32_bf16 v[54:57], v[146:149], v[162:165], 0
	v_mfma_f32_16x16x32_bf16 v[50:53], v[154:157], v[162:165], 0
	v_mfma_f32_16x16x32_bf16 v[38:41], v[146:149], v[170:173], 0
	v_mfma_f32_16x16x32_bf16 v[34:37], v[154:157], v[170:173], 0
	v_mfma_f32_16x16x32_bf16 v[22:25], v[146:149], v[208:211], 0
	v_mfma_f32_16x16x32_bf16 v[18:21], v[154:157], v[208:211], 0
	v_mfma_f32_16x16x32_bf16 v[6:9], v[146:149], v[220:223], 0
	v_mfma_f32_16x16x32_bf16 v[2:5], v[154:157], v[220:223], 0
	v_mfma_f32_16x16x32_bf16 v[54:57], v[150:153], v[166:169], v[54:57]
	v_mfma_f32_16x16x32_bf16 v[50:53], v[158:161], v[166:169], v[50:53]
	v_mfma_f32_16x16x32_bf16 v[38:41], v[150:153], v[174:177], v[38:41]
	v_mfma_f32_16x16x32_bf16 v[34:37], v[158:161], v[174:177], v[34:37]
	v_mfma_f32_16x16x32_bf16 v[22:25], v[150:153], v[212:215], v[22:25]
	v_mfma_f32_16x16x32_bf16 v[18:21], v[158:161], v[212:215], v[18:21]
	v_mfma_f32_16x16x32_bf16 v[6:9], v[150:153], v[224:227], v[6:9]
	v_mfma_f32_16x16x32_bf16 v[2:5], v[158:161], v[224:227], v[2:5]
	s_barrier
	s_setprio 0
	s_add_i32 s79, 0, 0x18000
	s_add_i32 s80, 0, 0x1c000
	v_add_u32_e32 v142, s79, v199
	v_add_u32_e32 v158, s80, v199
	ds_read_b128 v[130:133], v142
	ds_read_b128 v[134:137], v142 offset:1024
	ds_read_b128 v[138:141], v142 offset:2048
	ds_read_b128 v[142:145], v142 offset:3072
	ds_read_b128 v[146:149], v158
	ds_read_b128 v[150:153], v158 offset:1024
	ds_read_b128 v[154:157], v158 offset:2048
	ds_read_b128 v[158:161], v158 offset:3072
	s_add_u32 s72, s72, 0x4000
	s_addc_u32 s73, s73, 0
	s_mov_b32 m0, s56
	ds_read_b128 v[162:165], v203 offset:32768
	ds_read_b128 v[166:169], v203 offset:33792
	ds_read_b128 v[170:173], v203 offset:34816
	ds_read_b128 v[174:177], v203 offset:35840
	ds_read_b128 v[208:211], v203 offset:36864
	ds_read_b128 v[212:215], v203 offset:37888
	ds_read_b128 v[220:223], v203 offset:38912
	ds_read_b128 v[224:227], v203 offset:39936
	global_load_lds_dwordx4 v178, s[72:73]
	s_mov_b32 m0, s57
	s_nop 0
	global_load_lds_dwordx4 v182, s[72:73]
	s_waitcnt vmcnt(8)
	s_waitcnt lgkmcnt(0)
	s_setprio 1
	s_barrier
	v_mfma_f32_16x16x32_bf16 v[126:129], v[130:133], v[162:165], v[126:129]
	v_mfma_f32_16x16x32_bf16 v[122:125], v[138:141], v[162:165], v[122:125]
	v_mfma_f32_16x16x32_bf16 v[110:113], v[130:133], v[170:173], v[110:113]
	v_mfma_f32_16x16x32_bf16 v[106:109], v[138:141], v[170:173], v[106:109]
	v_mfma_f32_16x16x32_bf16 v[94:97], v[130:133], v[208:211], v[94:97]
	v_mfma_f32_16x16x32_bf16 v[90:93], v[138:141], v[208:211], v[90:93]
	v_mfma_f32_16x16x32_bf16 v[78:81], v[130:133], v[220:223], v[78:81]
	v_mfma_f32_16x16x32_bf16 v[74:77], v[138:141], v[220:223], v[74:77]
	v_mfma_f32_16x16x32_bf16 v[126:129], v[134:137], v[166:169], v[126:129]
	v_mfma_f32_16x16x32_bf16 v[122:125], v[142:145], v[166:169], v[122:125]
	v_mfma_f32_16x16x32_bf16 v[110:113], v[134:137], v[174:177], v[110:113]
	v_mfma_f32_16x16x32_bf16 v[106:109], v[142:145], v[174:177], v[106:109]
	v_mfma_f32_16x16x32_bf16 v[94:97], v[134:137], v[212:215], v[94:97]
	v_mfma_f32_16x16x32_bf16 v[90:93], v[142:145], v[212:215], v[90:93]
	v_mfma_f32_16x16x32_bf16 v[78:81], v[134:137], v[224:227], v[78:81]
	v_mfma_f32_16x16x32_bf16 v[74:77], v[142:145], v[224:227], v[74:77]
	s_setprio 0
	s_setprio 1
	v_mfma_f32_16x16x32_bf16 v[118:121], v[146:149], v[162:165], v[118:121]
	v_mfma_f32_16x16x32_bf16 v[114:117], v[154:157], v[162:165], v[114:117]
	v_mfma_f32_16x16x32_bf16 v[102:105], v[146:149], v[170:173], v[102:105]
	v_mfma_f32_16x16x32_bf16 v[98:101], v[154:157], v[170:173], v[98:101]
	v_mfma_f32_16x16x32_bf16 v[86:89], v[146:149], v[208:211], v[86:89]
	v_mfma_f32_16x16x32_bf16 v[82:85], v[154:157], v[208:211], v[82:85]
	v_mfma_f32_16x16x32_bf16 v[70:73], v[146:149], v[220:223], v[70:73]
	v_mfma_f32_16x16x32_bf16 v[66:69], v[154:157], v[220:223], v[66:69]
	v_mfma_f32_16x16x32_bf16 v[118:121], v[150:153], v[166:169], v[118:121]
	v_mfma_f32_16x16x32_bf16 v[114:117], v[158:161], v[166:169], v[114:117]
	v_mfma_f32_16x16x32_bf16 v[102:105], v[150:153], v[174:177], v[102:105]
	v_mfma_f32_16x16x32_bf16 v[98:101], v[158:161], v[174:177], v[98:101]
	v_mfma_f32_16x16x32_bf16 v[86:89], v[150:153], v[212:215], v[86:89]
	v_mfma_f32_16x16x32_bf16 v[82:85], v[158:161], v[212:215], v[82:85]
	v_mfma_f32_16x16x32_bf16 v[70:73], v[150:153], v[224:227], v[70:73]
	v_mfma_f32_16x16x32_bf16 v[66:69], v[158:161], v[224:227], v[66:69]
	s_barrier
; #define PG8_STAGE(bufoff, gbase, voff) do { _Pragma("unroll") for (int _i = 0; _i < 2; ++_i) \
;         __builtin_amdgcn_global_load_lds((const unsigned*)((const char*)(gbase) + (voff)[_i]), (PG8_LAS unsigned*)(lds + (bufoff) + ldsw + _i * 8192), 16, 0, 0); } while (0)
; #define PG8_LDA(dst, b, h) do { _Pragma("unroll") for (int m = 0; m < 4; ++m) _Pragma("unroll") for (int k = 0; k < 2; ++k) dst[m][k] = *(const PG8_LAS bf16x8*)(lds + PG8_SA(b, h) + aoff + m * 2048 + k * 1024); } while (0)
; #define PG8_MMA(ai, bj, At, Bt) do { __builtin_amdgcn_s_setprio(1); _Pragma("unroll") for (int m = 0; m < 4; ++m) _Pragma("unroll") for (int n = 0; n < 2; ++n) _Pragma("unroll") for (int k = 0; k < 2; ++k) \
;         acc[ai][bj][m][n] = __builtin_amdgcn_mfma_f32_16x16x32_bf16(Bt[n][k], At[m][k], acc[ai][bj][m][n], 0, 0, 0); __builtin_amdgcn_s_setprio(0); } while (0)
; #define PG8_WAIT_V(n) asm volatile("s_waitcnt vmcnt(" #n ")" ::: "memory")
; #define PG8_WAIT_L(n) asm volatile("s_waitcnt lgkmcnt(" #n ")" ::: "memory")
; #define PG8_BAR __builtin_amdgcn_s_barrier()
; #define PG8_SCHED __builtin_amdgcn_sched_barrier(0)
; template <class Epi, class Sched, bool ALIGN_EPI = false, bool SP2 = false>
; __device__ __forceinline__ void gemm_phase(PG8_LAS unsigned char* lds, const Gemm g, const Sched& S, const Epi& E) {
;     ...
;             PG8_LDA(At, 1, 1); PG8_STAGE(PG8_SB(1, 0), b3, voffB); PG8_STAGE(PG8_SB(1, 1), b3 + hstepB, voffB); PG8_STAGE(PG8_SA(1, 0), a3, voffA);
;             PG8_WAIT_V(8); PG8_WAIT_L(0); PG8_BAR; PG8_MMA(1, 0, At, B0); PG8_MMA(1, 1, At, B1); PG8_BAR; PG8_SCHED;
	s_setprio 0
	s_add_u32 s72, s70, 0x8000
	s_addc_u32 s73, s71, 0
	s_add_i32 s79, s79, s0
	s_mov_b32 m0, s79
	ds_read_b128 v[162:165], v203 offset:49152
	ds_read_b128 v[166:169], v203 offset:50176
	ds_read_b128 v[170:173], v203 offset:51200
	ds_read_b128 v[174:177], v203 offset:52224
	ds_read_b128 v[208:211], v203 offset:53248
	ds_read_b128 v[212:215], v203 offset:54272
	ds_read_b128 v[220:223], v203 offset:55296
	ds_read_b128 v[224:227], v203 offset:56320
	global_load_lds_dwordx4 v180, s[72:73]
	s_add_i32 m0, s79, 0x2000
	s_add_u32 s70, s70, 0x9000
	v_lshl_add_u64 v[196:197], s[72:73], 0, v[184:185]
	s_addc_u32 s71, s71, 0
	s_add_i32 s72, s80, s0
	global_load_lds_dwordx4 v[196:197], off
	s_mov_b32 m0, s72
	s_nop 0
	global_load_lds_dwordx4 v180, s[70:71]
	s_add_i32 m0, s72, 0x2000
	s_nop 0
	global_load_lds_dwordx4 v184, s[70:71]
	s_mov_b32 m0, s59
	s_nop 0
	global_load_lds_dwordx4 v178, s[68:69]
	s_mov_b32 m0, s74
	s_nop 0
	global_load_lds_dwordx4 v182, s[68:69]
	s_waitcnt vmcnt(8)
	s_waitcnt lgkmcnt(0)
	s_setprio 1
	s_barrier
	v_mfma_f32_16x16x32_bf16 v[62:65], v[130:133], v[162:165], v[62:65]
	v_mfma_f32_16x16x32_bf16 v[58:61], v[138:141], v[162:165], v[58:61]
	v_mfma_f32_16x16x32_bf16 v[46:49], v[130:133], v[170:173], v[46:49]
	v_mfma_f32_16x16x32_bf16 v[42:45], v[138:141], v[170:173], v[42:45]
	v_mfma_f32_16x16x32_bf16 v[30:33], v[130:133], v[208:211], v[30:33]
	v_mfma_f32_16x16x32_bf16 v[26:29], v[138:141], v[208:211], v[26:29]
	v_mfma_f32_16x16x32_bf16 v[14:17], v[130:133], v[220:223], v[14:17]
	v_mfma_f32_16x16x32_bf16 v[10:13], v[138:141], v[220:223], v[10:13]
	v_mfma_f32_16x16x32_bf16 v[62:65], v[134:137], v[166:169], v[62:65]
	v_mfma_f32_16x16x32_bf16 v[58:61], v[142:145], v[166:169], v[58:61]
	v_mfma_f32_16x16x32_bf16 v[46:49], v[134:137], v[174:177], v[46:49]
	v_mfma_f32_16x16x32_bf16 v[42:45], v[142:145], v[174:177], v[42:45]
	v_mfma_f32_16x16x32_bf16 v[30:33], v[134:137], v[212:215], v[30:33]
	v_mfma_f32_16x16x32_bf16 v[26:29], v[142:145], v[212:215], v[26:29]
	v_mfma_f32_16x16x32_bf16 v[14:17], v[134:137], v[224:227], v[14:17]
	v_mfma_f32_16x16x32_bf16 v[10:13], v[142:145], v[224:227], v[10:13]
	s_setprio 0
	s_setprio 1
	v_mfma_f32_16x16x32_bf16 v[54:57], v[146:149], v[162:165], v[54:57]
	v_mfma_f32_16x16x32_bf16 v[50:53], v[154:157], v[162:165], v[50:53]
	v_mfma_f32_16x16x32_bf16 v[38:41], v[146:149], v[170:173], v[38:41]
	v_mfma_f32_16x16x32_bf16 v[34:37], v[154:157], v[170:173], v[34:37]
	v_mfma_f32_16x16x32_bf16 v[22:25], v[146:149], v[208:211], v[22:25]
	v_mfma_f32_16x16x32_bf16 v[18:21], v[154:157], v[208:211], v[18:21]
	v_mfma_f32_16x16x32_bf16 v[6:9], v[146:149], v[220:223], v[6:9]
	v_mfma_f32_16x16x32_bf16 v[2:5], v[154:157], v[220:223], v[2:5]
	v_mfma_f32_16x16x32_bf16 v[54:57], v[150:153], v[166:169], v[54:57]
	v_mfma_f32_16x16x32_bf16 v[50:53], v[158:161], v[166:169], v[50:53]
	v_mfma_f32_16x16x32_bf16 v[38:41], v[150:153], v[174:177], v[38:41]
	v_mfma_f32_16x16x32_bf16 v[34:37], v[158:161], v[174:177], v[34:37]
	v_mfma_f32_16x16x32_bf16 v[22:25], v[150:153], v[212:215], v[22:25]
	v_mfma_f32_16x16x32_bf16 v[18:21], v[158:161], v[212:215], v[18:21]
	v_mfma_f32_16x16x32_bf16 v[6:9], v[150:153], v[224:227], v[6:9]
	v_mfma_f32_16x16x32_bf16 v[2:5], v[158:161], v[224:227], v[2:5]
	s_barrier
	s_setprio 0
	s_add_i32 s55, s55, 2
	s_add_u32 s50, s50, 0x10000
	s_addc_u32 s51, s51, 0
	s_add_u32 s53, s53, 0x10000
	s_addc_u32 s54, s54, 0
	.p2align 6

; #define PG8_STAGE(bufoff, gbase, voff) do { _Pragma("unroll") for (int _i = 0; _i < 2; ++_i) \
;         __builtin_amdgcn_global_load_lds((const unsigned*)((const char*)(gbase) + (voff)[_i]), (PG8_LAS unsigned*)(lds + (bufoff) + ldsw + _i * 8192), 16, 0, 0); } while (0)
; #define PG8_LDA(dst, b, h) do { _Pragma("unroll") for (int m = 0; m < 4; ++m) _Pragma("unroll") for (int k = 0; k < 2; ++k) dst[m][k] = *(const PG8_LAS bf16x8*)(lds + PG8_SA(b, h) + aoff + m * 2048 + k * 1024); } while (0)
; #define PG8_LDB(dst, b, h) do { _Pragma("unroll") for (int n = 0; n < 2; ++n) _Pragma("unroll") for (int k = 0; k < 2; ++k) dst[n][k] = *(const PG8_LAS bf16x8*)(lds + PG8_SB(b, h) + boff + n * 2048 + k * 1024); } while (0)
; #define PG8_WAIT_V(n) asm volatile("s_waitcnt vmcnt(" #n ")" ::: "memory")
; #define PG8_WAIT_L(n) asm volatile("s_waitcnt lgkmcnt(" #n ")" ::: "memory")
; #define PG8_BAR __builtin_amdgcn_s_barrier()
; template <class Epi, class Sched, bool ALIGN_EPI = false, bool SP2 = false>
; __device__ __forceinline__ void gemm_phase(PG8_LAS unsigned char* lds, const Gemm g, const Sched& S, const Epi& E) {
;     ...
;         const bool has_next = S.next(ui + 1, nxt);
;         const char* nA = has_next ? (const char*)g.A + (size_t)nxt.pm * tstep : cA; const char* nB = has_next ? (const char*)g.Bt + (size_t)nxt.pn * tstep : cB;
;         for (int t = 0; t < nt; t += 2) {
;             if constexpr (Epi::HAS_MID) { if (t == (nt >> 1)) E.mid(acc, cur, wr, wc, fr, fq); }
;             const bool last = (t == nt - 2);
;             const char* a1 = cA + (size_t)(t + 1) * kstep;
;             const char* a2 = last ? nA : cA + (size_t)(t + 2) * kstep; const char* b2 = last ? nB : cB + (size_t)(t + 2) * kstep;
;             const char* a3 = a2 + kstep; const char* b3 = b2 + kstep;
;             if (last && has_next) S.a_ready(nxt);
;             if constexpr (SP2) {
;             PG8_LDB(B0, 0, 0); PG8_LDB(B1, 0, 1); PG8_SCHED; PG8_LDA(At, 0, 0); PG8_STAGE(PG8_SA(1, 1), a1 + hstep, voffA);
;             PG8_WAIT_V(8); PG8_WAIT_L(0); PG8_BAR; PG8_MMA(0, 0, At, B0); PG8_MMA(0, 1, At, B1); PG8_BAR; PG8_SCHED;
;             PG8_LDA(At, 0, 1); PG8_STAGE(PG8_SB(0, 0), b2, voffB); PG8_STAGE(PG8_SB(0, 1), b2 + hstepB, voffB); PG8_STAGE(PG8_SA(0, 0), a2, voffA);
;             PG8_WAIT_V(8); PG8_WAIT_L(0); PG8_BAR; PG8_MMA(1, 0, At, B0); PG8_MMA(1, 1, At, B1); PG8_BAR; PG8_SCHED;
.LBB0_585:
	s_ashr_i32 s19, s18, 31
	s_lshl_b64 s[20:21], s[18:19], 19
	s_add_u32 s20, s62, s20
	s_addc_u32 s21, s63, s21
	s_and_b64 s[22:23], s[4:5], exec
	s_cselect_b32 s19, s21, s27
	s_cselect_b32 s55, s20, s26
	s_ashr_i32 s17, s16, 31
	s_lshl_b64 s[22:23], s[16:17], 19
	s_add_u32 s22, s64, s22
	s_addc_u32 s23, s65, s23
	s_and_b64 s[36:37], s[4:5], exec
	s_cselect_b32 s17, s23, s29
	s_cselect_b32 s56, s22, s28
	s_add_u32 s26, s26, 0xc000
	s_addc_u32 s27, s27, 0
	s_add_u32 s57, s28, 0x10000
	s_addc_u32 s58, s29, 0
	s_mov_b32 s59, -2
	ds_read_b128 v[166:169], v153
	ds_read_b128 v[170:173], v153 offset:1024
	ds_read_b128 v[174:177], v153 offset:2048
	ds_read_b128 v[178:181], v153 offset:3072
	ds_read_b128 v[182:185], v154
	ds_read_b128 v[186:189], v154 offset:1024
	ds_read_b128 v[190:193], v154 offset:2048
	ds_read_b128 v[194:197], v154 offset:3072
	s_add_u32 s28, s26, 0x4000
	s_addc_u32 s29, s27, 0
	s_cmp_eq_u32 s59, 12
	s_cselect_b32 s42, s55, s28
	s_cselect_b32 s43, s19, s29
	s_cselect_b32 s36, s56, s57
	s_cselect_b32 s37, s17, s58
	s_add_u32 s28, s42, 0x8000
	s_addc_u32 s29, s43, 0
	s_add_i32 m0, s3, 0xc000
	ds_read_b128 v[198:201], v155
	ds_read_b128 v[202:205], v155 offset:1024
	ds_read_b128 v[206:209], v155 offset:2048
	ds_read_b128 v[210:213], v155 offset:3072
	ds_read_b128 v[214:217], v155 offset:4096
	ds_read_b128 v[220:223], v155 offset:5120
	ds_read_b128 v[224:227], v155 offset:6144
	ds_read_b128 v[228:231], v155 offset:7168
	global_load_lds_dwordx4 v142, s[26:27]
	s_add_i32 m0, s3, 0xe000
	s_nop 0
	global_load_lds_dwordx4 v144, s[26:27]
	s_waitcnt vmcnt(8)
	s_waitcnt lgkmcnt(0)
	s_setprio 1
	s_barrier
	v_mfma_f32_16x16x32_bf16 v[126:129], v[166:169], v[198:201], 0
	v_mfma_f32_16x16x32_bf16 v[122:125], v[174:177], v[198:201], 0
	v_mfma_f32_16x16x32_bf16 v[110:113], v[166:169], v[206:209], 0
	v_mfma_f32_16x16x32_bf16 v[106:109], v[174:177], v[206:209], 0
	v_mfma_f32_16x16x32_bf16 v[94:97], v[166:169], v[214:217], 0
	v_mfma_f32_16x16x32_bf16 v[90:93], v[174:177], v[214:217], 0
	v_mfma_f32_16x16x32_bf16 v[78:81], v[166:169], v[224:227], 0
	v_mfma_f32_16x16x32_bf16 v[74:77], v[174:177], v[224:227], 0
	v_mfma_f32_16x16x32_bf16 v[126:129], v[170:173], v[202:205], v[126:129]
	v_mfma_f32_16x16x32_bf16 v[122:125], v[178:181], v[202:205], v[122:125]
	v_mfma_f32_16x16x32_bf16 v[110:113], v[170:173], v[210:213], v[110:113]
	v_mfma_f32_16x16x32_bf16 v[106:109], v[178:181], v[210:213], v[106:109]
	v_mfma_f32_16x16x32_bf16 v[94:97], v[170:173], v[220:223], v[94:97]
	v_mfma_f32_16x16x32_bf16 v[90:93], v[178:181], v[220:223], v[90:93]
	v_mfma_f32_16x16x32_bf16 v[78:81], v[170:173], v[228:231], v[78:81]
	v_mfma_f32_16x16x32_bf16 v[74:77], v[178:181], v[228:231], v[74:77]
	s_setprio 0
	s_setprio 1
	v_mfma_f32_16x16x32_bf16 v[118:121], v[182:185], v[198:201], 0
	v_mfma_f32_16x16x32_bf16 v[114:117], v[190:193], v[198:201], 0
	v_mfma_f32_16x16x32_bf16 v[102:105], v[182:185], v[206:209], 0
	v_mfma_f32_16x16x32_bf16 v[98:101], v[190:193], v[206:209], 0
	v_mfma_f32_16x16x32_bf16 v[86:89], v[182:185], v[214:217], 0
	v_mfma_f32_16x16x32_bf16 v[82:85], v[190:193], v[214:217], 0
	v_mfma_f32_16x16x32_bf16 v[70:73], v[182:185], v[224:227], 0
	v_mfma_f32_16x16x32_bf16 v[66:69], v[190:193], v[224:227], 0
	v_mfma_f32_16x16x32_bf16 v[118:121], v[186:189], v[202:205], v[118:121]
	v_mfma_f32_16x16x32_bf16 v[114:117], v[194:197], v[202:205], v[114:117]
	v_mfma_f32_16x16x32_bf16 v[102:105], v[186:189], v[210:213], v[102:105]
	v_mfma_f32_16x16x32_bf16 v[98:101], v[194:197], v[210:213], v[98:101]
	v_mfma_f32_16x16x32_bf16 v[86:89], v[186:189], v[220:223], v[86:89]
	v_mfma_f32_16x16x32_bf16 v[82:85], v[194:197], v[220:223], v[82:85]
	v_mfma_f32_16x16x32_bf16 v[70:73], v[186:189], v[228:231], v[70:73]
	v_mfma_f32_16x16x32_bf16 v[66:69], v[194:197], v[228:231], v[66:69]
	s_barrier
	s_setprio 0
	s_add_i32 s66, s8, s1
	s_mov_b32 m0, s66
	ds_read_b128 v[198:201], v155 offset:16384
	ds_read_b128 v[202:205], v155 offset:17408
	ds_read_b128 v[206:209], v155 offset:18432
	ds_read_b128 v[210:213], v155 offset:19456
	ds_read_b128 v[214:217], v155 offset:20480
	ds_read_b128 v[220:223], v155 offset:21504
	ds_read_b128 v[224:227], v155 offset:22528
	ds_read_b128 v[228:231], v155 offset:23552
	global_load_lds_dwordx4 v132, s[36:37]
	s_add_i32 m0, s66, 0x2000
	s_add_u32 s66, s36, 0x1000
	s_addc_u32 s67, s37, 0
	s_add_i32 s68, s52, s1
	global_load_lds_dwordx4 v136, s[36:37]
	s_mov_b32 m0, s68
	s_nop 0
	global_load_lds_dwordx4 v132, s[66:67]
	s_add_i32 m0, s68, 0x2000
	s_nop 0
	global_load_lds_dwordx4 v136, s[66:67]
	s_mov_b32 m0, s3
	s_nop 0
	global_load_lds_dwordx4 v130, s[42:43]
	s_mov_b32 m0, s44
	s_nop 0
	global_load_lds_dwordx4 v134, s[42:43]
	s_waitcnt vmcnt(8)
	s_waitcnt lgkmcnt(0)
	s_setprio 1
	s_barrier
; #define PG8_STAGE(bufoff, gbase, voff) do { _Pragma("unroll") for (int _i = 0; _i < 2; ++_i) \
;         __builtin_amdgcn_global_load_lds((const unsigned*)((const char*)(gbase) + (voff)[_i]), (PG8_LAS unsigned*)(lds + (bufoff) + ldsw + _i * 8192), 16, 0, 0); } while (0)
; #define PG8_LDA(dst, b, h) do { _Pragma("unroll") for (int m = 0; m < 4; ++m) _Pragma("unroll") for (int k = 0; k < 2; ++k) dst[m][k] = *(const PG8_LAS bf16x8*)(lds + PG8_SA(b, h) + aoff + m * 2048 + k * 1024); } while (0)
; #define PG8_LDB(dst, b, h) do { _Pragma("unroll") for (int n = 0; n < 2; ++n) _Pragma("unroll") for (int k = 0; k < 2; ++k) dst[n][k] = *(const PG8_LAS bf16x8*)(lds + PG8_SB(b, h) + boff + n * 2048 + k * 1024); } while (0)
; #define PG8_MMA(ai, bj, At, Bt) do { __builtin_amdgcn_s_setprio(1); _Pragma("unroll") for (int m = 0; m < 4; ++m) _Pragma("unroll") for (int n = 0; n < 2; ++n) _Pragma("unroll") for (int k = 0; k < 2; ++k) \
;         acc[ai][bj][m][n] = __builtin_amdgcn_mfma_f32_16x16x32_bf16(Bt[n][k], At[m][k], acc[ai][bj][m][n], 0, 0, 0); __builtin_amdgcn_s_setprio(0); } while (0)
; #define PG8_WAIT_V(n) asm volatile("s_waitcnt vmcnt(" #n ")" ::: "memory")
; #define PG8_WAIT_L(n) asm volatile("s_waitcnt lgkmcnt(" #n ")" ::: "memory")
; #define PG8_BAR __builtin_amdgcn_s_barrier()
; #define PG8_SCHED __builtin_amdgcn_sched_barrier(0)
; template <class Epi, class Sched, bool ALIGN_EPI = false, bool SP2 = false>
; __device__ __forceinline__ void gemm_phase(PG8_LAS unsigned char* lds, const Gemm g, const Sched& S, const Epi& E) {
;     ...
;             PG8_WAIT_V(8); PG8_WAIT_L(0); PG8_BAR; PG8_MMA(1, 0, At, B0); PG8_MMA(1, 1, At, B1); PG8_BAR; PG8_SCHED;
;             PG8_LDB(B0, 1, 0); PG8_LDB(B1, 1, 1); PG8_SCHED; PG8_LDA(At, 1, 0); PG8_STAGE(PG8_SA(0, 1), a2 + hstep, voffA);
;             PG8_WAIT_V(8); PG8_WAIT_L(0); PG8_BAR; PG8_MMA(0, 0, At, B0); PG8_MMA(0, 1, At, B1); PG8_BAR; PG8_SCHED;
	v_mfma_f32_16x16x32_bf16 v[62:65], v[166:169], v[198:201], 0
	v_mfma_f32_16x16x32_bf16 v[58:61], v[174:177], v[198:201], 0
	v_mfma_f32_16x16x32_bf16 v[46:49], v[166:169], v[206:209], 0
	v_mfma_f32_16x16x32_bf16 v[42:45], v[174:177], v[206:209], 0
	v_mfma_f32_16x16x32_bf16 v[30:33], v[166:169], v[214:217], 0
	v_mfma_f32_16x16x32_bf16 v[26:29], v[174:177], v[214:217], 0
	v_mfma_f32_16x16x32_bf16 v[14:17], v[166:169], v[224:227], 0
	v_mfma_f32_16x16x32_bf16 v[10:13], v[174:177], v[224:227], 0
	v_mfma_f32_16x16x32_bf16 v[62:65], v[170:173], v[202:205], v[62:65]
	v_mfma_f32_16x16x32_bf16 v[58:61], v[178:181], v[202:205], v[58:61]
	v_mfma_f32_16x16x32_bf16 v[46:49], v[170:173], v[210:213], v[46:49]
	v_mfma_f32_16x16x32_bf16 v[42:45], v[178:181], v[210:213], v[42:45]
	v_mfma_f32_16x16x32_bf16 v[30:33], v[170:173], v[220:223], v[30:33]
	v_mfma_f32_16x16x32_bf16 v[26:29], v[178:181], v[220:223], v[26:29]
	v_mfma_f32_16x16x32_bf16 v[14:17], v[170:173], v[228:231], v[14:17]
	v_mfma_f32_16x16x32_bf16 v[10:13], v[178:181], v[228:231], v[10:13]
	s_setprio 0
	s_setprio 1
	v_mfma_f32_16x16x32_bf16 v[54:57], v[182:185], v[198:201], 0
	v_mfma_f32_16x16x32_bf16 v[50:53], v[190:193], v[198:201], 0
	v_mfma_f32_16x16x32_bf16 v[38:41], v[182:185], v[206:209], 0
	v_mfma_f32_16x16x32_bf16 v[34:37], v[190:193], v[206:209], 0
	v_mfma_f32_16x16x32_bf16 v[22:25], v[182:185], v[214:217], 0
	v_mfma_f32_16x16x32_bf16 v[18:21], v[190:193], v[214:217], 0
	v_mfma_f32_16x16x32_bf16 v[6:9], v[182:185], v[224:227], 0
	v_mfma_f32_16x16x32_bf16 v[2:5], v[190:193], v[224:227], 0
	v_mfma_f32_16x16x32_bf16 v[54:57], v[186:189], v[202:205], v[54:57]
	v_mfma_f32_16x16x32_bf16 v[50:53], v[194:197], v[202:205], v[50:53]
	v_mfma_f32_16x16x32_bf16 v[38:41], v[186:189], v[210:213], v[38:41]
	v_mfma_f32_16x16x32_bf16 v[34:37], v[194:197], v[210:213], v[34:37]
	v_mfma_f32_16x16x32_bf16 v[22:25], v[186:189], v[220:223], v[22:25]
	v_mfma_f32_16x16x32_bf16 v[18:21], v[194:197], v[220:223], v[18:21]
	v_mfma_f32_16x16x32_bf16 v[6:9], v[186:189], v[228:231], v[6:9]
	v_mfma_f32_16x16x32_bf16 v[2:5], v[194:197], v[228:231], v[2:5]
	s_barrier
	s_setprio 0
	s_add_i32 s66, 0, 0x18000
	v_add_u32_e32 v165, s66, v151
	s_add_i32 s67, 0, 0x1c000
	ds_read_b128 v[166:169], v165
	ds_read_b128 v[170:173], v165 offset:1024
	ds_read_b128 v[174:177], v165 offset:2048
	ds_read_b128 v[178:181], v165 offset:3072
	v_add_u32_e32 v165, s67, v151
	ds_read_b128 v[182:185], v165
	ds_read_b128 v[186:189], v165 offset:1024
	ds_read_b128 v[190:193], v165 offset:2048
	ds_read_b128 v[194:197], v165 offset:3072
	s_add_u32 s42, s42, 0x4000
	s_addc_u32 s43, s43, 0
	s_mov_b32 m0, s45
	ds_read_b128 v[198:201], v155 offset:32768
	ds_read_b128 v[202:205], v155 offset:33792
	ds_read_b128 v[206:209], v155 offset:34816
	ds_read_b128 v[210:213], v155 offset:35840
	ds_read_b128 v[214:217], v155 offset:36864
	ds_read_b128 v[220:223], v155 offset:37888
	ds_read_b128 v[224:227], v155 offset:38912
	ds_read_b128 v[228:231], v155 offset:39936
	global_load_lds_dwordx4 v130, s[42:43]
	s_mov_b32 m0, s46
	s_nop 0
	global_load_lds_dwordx4 v134, s[42:43]
	s_waitcnt vmcnt(8)
	s_waitcnt lgkmcnt(0)
	s_setprio 1
	s_barrier
	v_mfma_f32_16x16x32_bf16 v[126:129], v[166:169], v[198:201], v[126:129]
	v_mfma_f32_16x16x32_bf16 v[122:125], v[174:177], v[198:201], v[122:125]
	v_mfma_f32_16x16x32_bf16 v[110:113], v[166:169], v[206:209], v[110:113]
	v_mfma_f32_16x16x32_bf16 v[106:109], v[174:177], v[206:209], v[106:109]
	v_mfma_f32_16x16x32_bf16 v[94:97], v[166:169], v[214:217], v[94:97]
	v_mfma_f32_16x16x32_bf16 v[90:93], v[174:177], v[214:217], v[90:93]
	v_mfma_f32_16x16x32_bf16 v[78:81], v[166:169], v[224:227], v[78:81]
	v_mfma_f32_16x16x32_bf16 v[74:77], v[174:177], v[224:227], v[74:77]
	v_mfma_f32_16x16x32_bf16 v[126:129], v[170:173], v[202:205], v[126:129]
	v_mfma_f32_16x16x32_bf16 v[122:125], v[178:181], v[202:205], v[122:125]
	v_mfma_f32_16x16x32_bf16 v[110:113], v[170:173], v[210:213], v[110:113]
	v_mfma_f32_16x16x32_bf16 v[106:109], v[178:181], v[210:213], v[106:109]
	v_mfma_f32_16x16x32_bf16 v[94:97], v[170:173], v[220:223], v[94:97]
	v_mfma_f32_16x16x32_bf16 v[90:93], v[178:181], v[220:223], v[90:93]
	v_mfma_f32_16x16x32_bf16 v[78:81], v[170:173], v[228:231], v[78:81]
	v_mfma_f32_16x16x32_bf16 v[74:77], v[178:181], v[228:231], v[74:77]
	s_setprio 0
	s_setprio 1
	v_mfma_f32_16x16x32_bf16 v[118:121], v[182:185], v[198:201], v[118:121]
	v_mfma_f32_16x16x32_bf16 v[114:117], v[190:193], v[198:201], v[114:117]
	v_mfma_f32_16x16x32_bf16 v[102:105], v[182:185], v[206:209], v[102:105]
	v_mfma_f32_16x16x32_bf16 v[98:101], v[190:193], v[206:209], v[98:101]
	v_mfma_f32_16x16x32_bf16 v[86:89], v[182:185], v[214:217], v[86:89]
	v_mfma_f32_16x16x32_bf16 v[82:85], v[190:193], v[214:217], v[82:85]
	v_mfma_f32_16x16x32_bf16 v[70:73], v[182:185], v[224:227], v[70:73]
	v_mfma_f32_16x16x32_bf16 v[66:69], v[190:193], v[224:227], v[66:69]
	v_mfma_f32_16x16x32_bf16 v[118:121], v[186:189], v[202:205], v[118:121]
	v_mfma_f32_16x16x32_bf16 v[114:117], v[194:197], v[202:205], v[114:117]
	v_mfma_f32_16x16x32_bf16 v[102:105], v[186:189], v[210:213], v[102:105]
	v_mfma_f32_16x16x32_bf16 v[98:101], v[194:197], v[210:213], v[98:101]
	v_mfma_f32_16x16x32_bf16 v[86:89], v[186:189], v[220:223], v[86:89]
	v_mfma_f32_16x16x32_bf16 v[82:85], v[194:197], v[220:223], v[82:85]
	v_mfma_f32_16x16x32_bf16 v[70:73], v[186:189], v[228:231], v[70:73]
	v_mfma_f32_16x16x32_bf16 v[66:69], v[194:197], v[228:231], v[66:69]
	s_barrier
; #define PG8_STAGE(bufoff, gbase, voff) do { _Pragma("unroll") for (int _i = 0; _i < 2; ++_i) \
;         __builtin_amdgcn_global_load_lds((const unsigned*)((const char*)(gbase) + (voff)[_i]), (PG8_LAS unsigned*)(lds + (bufoff) + ldsw + _i * 8192), 16, 0, 0); } while (0)
; #define PG8_LDA(dst, b, h) do { _Pragma("unroll") for (int m = 0; m < 4; ++m) _Pragma("unroll") for (int k = 0; k < 2; ++k) dst[m][k] = *(const PG8_LAS bf16x8*)(lds + PG8_SA(b, h) + aoff + m * 2048 + k * 1024); } while (0)
; #define PG8_MMA(ai, bj, At, Bt) do { __builtin_amdgcn_s_setprio(1); _Pragma("unroll") for (int m = 0; m < 4; ++m) _Pragma("unroll") for (int n = 0; n < 2; ++n) _Pragma("unroll") for (int k = 0; k < 2; ++k) \
;         acc[ai][bj][m][n] = __builtin_amdgcn_mfma_f32_16x16x32_bf16(Bt[n][k], At[m][k], acc[ai][bj][m][n], 0, 0, 0); __builtin_amdgcn_s_setprio(0); } while (0)
; #define PG8_WAIT_V(n) asm volatile("s_waitcnt vmcnt(" #n ")" ::: "memory")
; #define PG8_WAIT_L(n) asm volatile("s_waitcnt lgkmcnt(" #n ")" ::: "memory")
; #define PG8_BAR __builtin_amdgcn_s_barrier()
; #define PG8_SCHED __builtin_amdgcn_sched_barrier(0)
; template <class Epi, class Sched, bool ALIGN_EPI = false, bool SP2 = false>
; __device__ __forceinline__ void gemm_phase(PG8_LAS unsigned char* lds, const Gemm g, const Sched& S, const Epi& E) {
;     ...
;             PG8_LDA(At, 1, 1); PG8_STAGE(PG8_SB(1, 0), b3, voffB); PG8_STAGE(PG8_SB(1, 1), b3 + hstepB, voffB); PG8_STAGE(PG8_SA(1, 0), a3, voffA);
;             PG8_WAIT_V(8); PG8_WAIT_L(0); PG8_BAR; PG8_MMA(1, 0, At, B0); PG8_MMA(1, 1, At, B1); PG8_BAR; PG8_SCHED;
	s_setprio 0
	s_add_u32 s42, s36, 0x8000
	s_addc_u32 s43, s37, 0
	s_add_i32 s66, s66, s1
	s_mov_b32 m0, s66
	ds_read_b128 v[198:201], v155 offset:49152
	ds_read_b128 v[202:205], v155 offset:50176
	ds_read_b128 v[206:209], v155 offset:51200
	ds_read_b128 v[210:213], v155 offset:52224
	ds_read_b128 v[214:217], v155 offset:53248
	ds_read_b128 v[220:223], v155 offset:54272
	ds_read_b128 v[224:227], v155 offset:55296
	ds_read_b128 v[228:231], v155 offset:56320
	global_load_lds_dwordx4 v132, s[42:43]
	s_add_i32 m0, s66, 0x2000
	s_add_u32 s36, s36, 0x9000
	v_lshl_add_u64 v[232:233], s[42:43], 0, v[136:137]
	s_addc_u32 s37, s37, 0
	s_add_i32 s42, s67, s1
	global_load_lds_dwordx4 v[232:233], off
	s_mov_b32 m0, s42
	s_nop 0
	global_load_lds_dwordx4 v132, s[36:37]
	s_add_i32 m0, s42, 0x2000
	s_nop 0
	global_load_lds_dwordx4 v136, s[36:37]
	s_mov_b32 m0, s49
	s_nop 0
	global_load_lds_dwordx4 v130, s[28:29]
	s_mov_b32 m0, s50
	s_nop 0
	global_load_lds_dwordx4 v134, s[28:29]
	s_waitcnt vmcnt(8)
	s_waitcnt lgkmcnt(0)
	s_setprio 1
	s_barrier
	v_mfma_f32_16x16x32_bf16 v[62:65], v[166:169], v[198:201], v[62:65]
	v_mfma_f32_16x16x32_bf16 v[58:61], v[174:177], v[198:201], v[58:61]
	v_mfma_f32_16x16x32_bf16 v[46:49], v[166:169], v[206:209], v[46:49]
	v_mfma_f32_16x16x32_bf16 v[42:45], v[174:177], v[206:209], v[42:45]
	v_mfma_f32_16x16x32_bf16 v[30:33], v[166:169], v[214:217], v[30:33]
	v_mfma_f32_16x16x32_bf16 v[26:29], v[174:177], v[214:217], v[26:29]
	v_mfma_f32_16x16x32_bf16 v[14:17], v[166:169], v[224:227], v[14:17]
	v_mfma_f32_16x16x32_bf16 v[10:13], v[174:177], v[224:227], v[10:13]
	v_mfma_f32_16x16x32_bf16 v[62:65], v[170:173], v[202:205], v[62:65]
	v_mfma_f32_16x16x32_bf16 v[58:61], v[178:181], v[202:205], v[58:61]
	v_mfma_f32_16x16x32_bf16 v[46:49], v[170:173], v[210:213], v[46:49]
	v_mfma_f32_16x16x32_bf16 v[42:45], v[178:181], v[210:213], v[42:45]
	v_mfma_f32_16x16x32_bf16 v[30:33], v[170:173], v[220:223], v[30:33]
	v_mfma_f32_16x16x32_bf16 v[26:29], v[178:181], v[220:223], v[26:29]
	v_mfma_f32_16x16x32_bf16 v[14:17], v[170:173], v[228:231], v[14:17]
	v_mfma_f32_16x16x32_bf16 v[10:13], v[178:181], v[228:231], v[10:13]
	s_setprio 0
	s_setprio 1
	v_mfma_f32_16x16x32_bf16 v[54:57], v[182:185], v[198:201], v[54:57]
	v_mfma_f32_16x16x32_bf16 v[50:53], v[190:193], v[198:201], v[50:53]
	v_mfma_f32_16x16x32_bf16 v[38:41], v[182:185], v[206:209], v[38:41]
	v_mfma_f32_16x16x32_bf16 v[34:37], v[190:193], v[206:209], v[34:37]
	v_mfma_f32_16x16x32_bf16 v[22:25], v[182:185], v[214:217], v[22:25]
	v_mfma_f32_16x16x32_bf16 v[18:21], v[190:193], v[214:217], v[18:21]
	v_mfma_f32_16x16x32_bf16 v[6:9], v[182:185], v[224:227], v[6:9]
	v_mfma_f32_16x16x32_bf16 v[2:5], v[190:193], v[224:227], v[2:5]
	v_mfma_f32_16x16x32_bf16 v[54:57], v[186:189], v[202:205], v[54:57]
	v_mfma_f32_16x16x32_bf16 v[50:53], v[194:197], v[202:205], v[50:53]
	v_mfma_f32_16x16x32_bf16 v[38:41], v[186:189], v[210:213], v[38:41]
	v_mfma_f32_16x16x32_bf16 v[34:37], v[194:197], v[210:213], v[34:37]
	v_mfma_f32_16x16x32_bf16 v[22:25], v[186:189], v[220:223], v[22:25]
	v_mfma_f32_16x16x32_bf16 v[18:21], v[194:197], v[220:223], v[18:21]
	v_mfma_f32_16x16x32_bf16 v[6:9], v[186:189], v[228:231], v[6:9]
	v_mfma_f32_16x16x32_bf16 v[2:5], v[194:197], v[228:231], v[2:5]
	s_barrier
	s_setprio 0
	s_add_i32 s59, s59, 2
	s_add_u32 s26, s26, 0x10000
	s_addc_u32 s27, s27, 0
	s_add_u32 s57, s57, 0x10000
	s_addc_u32 s58, s58, 0
	.p2align 6

; #define PG8_STAGE(bufoff, gbase, voff) do { _Pragma("unroll") for (int _i = 0; _i < 2; ++_i) \
;         __builtin_amdgcn_global_load_lds((const unsigned*)((const char*)(gbase) + (voff)[_i]), (PG8_LAS unsigned*)(lds + (bufoff) + ldsw + _i * 8192), 16, 0, 0); } while (0)
; #define PG8_LDA(dst, b, h) do { _Pragma("unroll") for (int m = 0; m < 4; ++m) _Pragma("unroll") for (int k = 0; k < 2; ++k) dst[m][k] = *(const PG8_LAS bf16x8*)(lds + PG8_SA(b, h) + aoff + m * 2048 + k * 1024); } while (0)
; #define PG8_LDB(dst, b, h) do { _Pragma("unroll") for (int n = 0; n < 2; ++n) _Pragma("unroll") for (int k = 0; k < 2; ++k) dst[n][k] = *(const PG8_LAS bf16x8*)(lds + PG8_SB(b, h) + boff + n * 2048 + k * 1024); } while (0)
; #define PG8_WAIT_V(n) asm volatile("s_waitcnt vmcnt(" #n ")" ::: "memory")
; #define PG8_WAIT_L(n) asm volatile("s_waitcnt lgkmcnt(" #n ")" ::: "memory")
; #define PG8_BAR __builtin_amdgcn_s_barrier()
; template <class Epi, class Sched, bool ALIGN_EPI = false, bool SP2 = false>
; __device__ __forceinline__ void gemm_phase(PG8_LAS unsigned char* lds, const Gemm g, const Sched& S, const Epi& E) {
;     ...
;         const bool has_next = S.next(ui + 1, nxt);
;         const char* nA = has_next ? (const char*)g.A + (size_t)nxt.pm * tstep : cA; const char* nB = has_next ? (const char*)g.Bt + (size_t)nxt.pn * tstep : cB;
;         for (int t = 0; t < nt; t += 2) {
;             if constexpr (Epi::HAS_MID) { if (t == (nt >> 1)) E.mid(acc, cur, wr, wc, fr, fq); }
;             const bool last = (t == nt - 2);
;             const char* a1 = cA + (size_t)(t + 1) * kstep;
;             const char* a2 = last ? nA : cA + (size_t)(t + 2) * kstep; const char* b2 = last ? nB : cB + (size_t)(t + 2) * kstep;
;             const char* a3 = a2 + kstep; const char* b3 = b2 + kstep;
;             if (last && has_next) S.a_ready(nxt);
;             if constexpr (SP2) {
;             PG8_LDB(B0, 0, 0); PG8_LDB(B1, 0, 1); PG8_SCHED; PG8_LDA(At, 0, 0); PG8_STAGE(PG8_SA(1, 1), a1 + hstep, voffA);
;             PG8_WAIT_V(8); PG8_WAIT_L(0); PG8_BAR; PG8_MMA(0, 0, At, B0); PG8_MMA(0, 1, At, B1); PG8_BAR; PG8_SCHED;
;             PG8_LDA(At, 0, 1); PG8_STAGE(PG8_SB(0, 0), b2, voffB); PG8_STAGE(PG8_SB(0, 1), b2 + hstepB, voffB); PG8_STAGE(PG8_SA(0, 0), a2, voffA);
;             PG8_WAIT_V(8); PG8_WAIT_L(0); PG8_BAR; PG8_MMA(1, 0, At, B0); PG8_MMA(1, 1, At, B1); PG8_BAR; PG8_SCHED;
.LBB0_725:
	s_ashr_i32 s29, s28, 31
	s_lshl_b64 s[42:43], s[28:29], 21
	s_add_u32 s42, s38, s42
	s_addc_u32 s43, s39, s43
	s_and_b64 s[44:45], s[6:7], exec
	s_cselect_b32 s27, s43, s51
	s_cselect_b32 s29, s42, s50
	s_ashr_i32 s37, s36, 31
	s_lshl_b64 s[44:45], s[36:37], 21
	s_add_u32 s44, s60, s44
	s_addc_u32 s45, s61, s45
	s_and_b64 s[52:53], s[6:7], exec
	s_cselect_b32 s37, s45, s65
	s_cselect_b32 s47, s44, s64
	s_add_u32 s50, s50, 0xc000
	s_addc_u32 s51, s51, 0
	s_add_u32 s49, s64, 0x10000
	s_addc_u32 s52, s65, 0
	s_mov_b32 s53, -2
	ds_read_b128 v[130:133], v209
	ds_read_b128 v[134:137], v209 offset:1024
	ds_read_b128 v[138:141], v209 offset:2048
	ds_read_b128 v[142:145], v209 offset:3072
	ds_read_b128 v[146:149], v210
	ds_read_b128 v[150:153], v210 offset:1024
	ds_read_b128 v[154:157], v210 offset:2048
	ds_read_b128 v[158:161], v210 offset:3072
	s_add_u32 s54, s50, 0x4000
	s_addc_u32 s55, s51, 0
	s_cmp_eq_u32 s53, 60
	s_cselect_b32 s68, s29, s54
	s_cselect_b32 s69, s27, s55
	s_cselect_b32 s66, s47, s49
	s_cselect_b32 s67, s37, s52
	s_add_u32 s64, s68, 0x8000
	s_addc_u32 s65, s69, 0
	s_add_i32 m0, s1, 0xc000
	ds_read_b128 v[162:165], v211
	ds_read_b128 v[166:169], v211 offset:1024
	ds_read_b128 v[170:173], v211 offset:2048
	ds_read_b128 v[174:177], v211 offset:3072
	ds_read_b128 v[178:181], v211 offset:4096
	ds_read_b128 v[182:185], v211 offset:5120
	ds_read_b128 v[224:227], v211 offset:6144
	ds_read_b128 v[228:231], v211 offset:7168
	global_load_lds_dwordx4 v198, s[50:51]
	s_add_i32 m0, s1, 0xe000
	s_nop 0
	global_load_lds_dwordx4 v200, s[50:51]
	s_waitcnt vmcnt(8)
	s_waitcnt lgkmcnt(0)
	s_setprio 1
	s_barrier
	v_mfma_f32_16x16x32_bf16 v[126:129], v[130:133], v[162:165], 0
	v_mfma_f32_16x16x32_bf16 v[122:125], v[138:141], v[162:165], 0
	v_mfma_f32_16x16x32_bf16 v[110:113], v[130:133], v[170:173], 0
	v_mfma_f32_16x16x32_bf16 v[106:109], v[138:141], v[170:173], 0
	v_mfma_f32_16x16x32_bf16 v[94:97], v[130:133], v[178:181], 0
	v_mfma_f32_16x16x32_bf16 v[90:93], v[138:141], v[178:181], 0
	v_mfma_f32_16x16x32_bf16 v[78:81], v[130:133], v[224:227], 0
	v_mfma_f32_16x16x32_bf16 v[74:77], v[138:141], v[224:227], 0
	v_mfma_f32_16x16x32_bf16 v[126:129], v[134:137], v[166:169], v[126:129]
	v_mfma_f32_16x16x32_bf16 v[122:125], v[142:145], v[166:169], v[122:125]
	v_mfma_f32_16x16x32_bf16 v[110:113], v[134:137], v[174:177], v[110:113]
	v_mfma_f32_16x16x32_bf16 v[106:109], v[142:145], v[174:177], v[106:109]
	v_mfma_f32_16x16x32_bf16 v[94:97], v[134:137], v[182:185], v[94:97]
	v_mfma_f32_16x16x32_bf16 v[90:93], v[142:145], v[182:185], v[90:93]
	v_mfma_f32_16x16x32_bf16 v[78:81], v[134:137], v[228:231], v[78:81]
	v_mfma_f32_16x16x32_bf16 v[74:77], v[142:145], v[228:231], v[74:77]
	s_setprio 0
	s_setprio 1
	v_mfma_f32_16x16x32_bf16 v[118:121], v[146:149], v[162:165], 0
	v_mfma_f32_16x16x32_bf16 v[114:117], v[154:157], v[162:165], 0
	v_mfma_f32_16x16x32_bf16 v[102:105], v[146:149], v[170:173], 0
	v_mfma_f32_16x16x32_bf16 v[98:101], v[154:157], v[170:173], 0
	v_mfma_f32_16x16x32_bf16 v[86:89], v[146:149], v[178:181], 0
	v_mfma_f32_16x16x32_bf16 v[82:85], v[154:157], v[178:181], 0
	v_mfma_f32_16x16x32_bf16 v[70:73], v[146:149], v[224:227], 0
	v_mfma_f32_16x16x32_bf16 v[66:69], v[154:157], v[224:227], 0
	v_mfma_f32_16x16x32_bf16 v[118:121], v[150:153], v[166:169], v[118:121]
	v_mfma_f32_16x16x32_bf16 v[114:117], v[158:161], v[166:169], v[114:117]
	v_mfma_f32_16x16x32_bf16 v[102:105], v[150:153], v[174:177], v[102:105]
	v_mfma_f32_16x16x32_bf16 v[98:101], v[158:161], v[174:177], v[98:101]
	v_mfma_f32_16x16x32_bf16 v[86:89], v[150:153], v[182:185], v[86:89]
	v_mfma_f32_16x16x32_bf16 v[82:85], v[158:161], v[182:185], v[82:85]
	v_mfma_f32_16x16x32_bf16 v[70:73], v[150:153], v[228:231], v[70:73]
	v_mfma_f32_16x16x32_bf16 v[66:69], v[158:161], v[228:231], v[66:69]
	s_barrier
	s_setprio 0
	s_add_i32 s54, s74, s0
	s_mov_b32 m0, s54
	ds_read_b128 v[162:165], v211 offset:16384
	ds_read_b128 v[166:169], v211 offset:17408
	ds_read_b128 v[170:173], v211 offset:18432
	ds_read_b128 v[174:177], v211 offset:19456
	ds_read_b128 v[178:181], v211 offset:20480
	ds_read_b128 v[182:185], v211 offset:21504
	ds_read_b128 v[224:227], v211 offset:22528
	ds_read_b128 v[228:231], v211 offset:23552
	global_load_lds_dwordx4 v188, s[66:67]
	s_add_i32 m0, s54, 0x2000
	s_add_u32 s54, s66, 0x1000
	s_addc_u32 s55, s67, 0
	s_add_i32 s89, s75, s0
	global_load_lds_dwordx4 v192, s[66:67]
	s_mov_b32 m0, s89
	s_nop 0
	global_load_lds_dwordx4 v188, s[54:55]
	s_add_i32 m0, s89, 0x2000
	s_nop 0
	global_load_lds_dwordx4 v192, s[54:55]
	s_mov_b32 m0, s1
	s_nop 0
	global_load_lds_dwordx4 v186, s[68:69]
	s_mov_b32 m0, s3
	s_nop 0
	global_load_lds_dwordx4 v190, s[68:69]
	s_waitcnt vmcnt(8)
	s_waitcnt lgkmcnt(0)
	s_setprio 1
	s_barrier
; #define PG8_STAGE(bufoff, gbase, voff) do { _Pragma("unroll") for (int _i = 0; _i < 2; ++_i) \
;         __builtin_amdgcn_global_load_lds((const unsigned*)((const char*)(gbase) + (voff)[_i]), (PG8_LAS unsigned*)(lds + (bufoff) + ldsw + _i * 8192), 16, 0, 0); } while (0)
; #define PG8_LDA(dst, b, h) do { _Pragma("unroll") for (int m = 0; m < 4; ++m) _Pragma("unroll") for (int k = 0; k < 2; ++k) dst[m][k] = *(const PG8_LAS bf16x8*)(lds + PG8_SA(b, h) + aoff + m * 2048 + k * 1024); } while (0)
; #define PG8_LDB(dst, b, h) do { _Pragma("unroll") for (int n = 0; n < 2; ++n) _Pragma("unroll") for (int k = 0; k < 2; ++k) dst[n][k] = *(const PG8_LAS bf16x8*)(lds + PG8_SB(b, h) + boff + n * 2048 + k * 1024); } while (0)
; #define PG8_MMA(ai, bj, At, Bt) do { __builtin_amdgcn_s_setprio(1); _Pragma("unroll") for (int m = 0; m < 4; ++m) _Pragma("unroll") for (int n = 0; n < 2; ++n) _Pragma("unroll") for (int k = 0; k < 2; ++k) \
;         acc[ai][bj][m][n] = __builtin_amdgcn_mfma_f32_16x16x32_bf16(Bt[n][k], At[m][k], acc[ai][bj][m][n], 0, 0, 0); __builtin_amdgcn_s_setprio(0); } while (0)
; #define PG8_WAIT_V(n) asm volatile("s_waitcnt vmcnt(" #n ")" ::: "memory")
; #define PG8_WAIT_L(n) asm volatile("s_waitcnt lgkmcnt(" #n ")" ::: "memory")
; #define PG8_BAR __builtin_amdgcn_s_barrier()
; #define PG8_SCHED __builtin_amdgcn_sched_barrier(0)
; template <class Epi, class Sched, bool ALIGN_EPI = false, bool SP2 = false>
; __device__ __forceinline__ void gemm_phase(PG8_LAS unsigned char* lds, const Gemm g, const Sched& S, const Epi& E) {
;     ...
;             PG8_WAIT_V(8); PG8_WAIT_L(0); PG8_BAR; PG8_MMA(1, 0, At, B0); PG8_MMA(1, 1, At, B1); PG8_BAR; PG8_SCHED;
;             PG8_LDB(B0, 1, 0); PG8_LDB(B1, 1, 1); PG8_SCHED; PG8_LDA(At, 1, 0); PG8_STAGE(PG8_SA(0, 1), a2 + hstep, voffA);
;             PG8_WAIT_V(8); PG8_WAIT_L(0); PG8_BAR; PG8_MMA(0, 0, At, B0); PG8_MMA(0, 1, At, B1); PG8_BAR; PG8_SCHED;
	v_mfma_f32_16x16x32_bf16 v[62:65], v[130:133], v[162:165], 0
	v_mfma_f32_16x16x32_bf16 v[58:61], v[138:141], v[162:165], 0
	v_mfma_f32_16x16x32_bf16 v[46:49], v[130:133], v[170:173], 0
	v_mfma_f32_16x16x32_bf16 v[42:45], v[138:141], v[170:173], 0
	v_mfma_f32_16x16x32_bf16 v[30:33], v[130:133], v[178:181], 0
	v_mfma_f32_16x16x32_bf16 v[26:29], v[138:141], v[178:181], 0
	v_mfma_f32_16x16x32_bf16 v[14:17], v[130:133], v[224:227], 0
	v_mfma_f32_16x16x32_bf16 v[10:13], v[138:141], v[224:227], 0
	v_mfma_f32_16x16x32_bf16 v[62:65], v[134:137], v[166:169], v[62:65]
	v_mfma_f32_16x16x32_bf16 v[58:61], v[142:145], v[166:169], v[58:61]
	v_mfma_f32_16x16x32_bf16 v[46:49], v[134:137], v[174:177], v[46:49]
	v_mfma_f32_16x16x32_bf16 v[42:45], v[142:145], v[174:177], v[42:45]
	v_mfma_f32_16x16x32_bf16 v[30:33], v[134:137], v[182:185], v[30:33]
	v_mfma_f32_16x16x32_bf16 v[26:29], v[142:145], v[182:185], v[26:29]
	v_mfma_f32_16x16x32_bf16 v[14:17], v[134:137], v[228:231], v[14:17]
	v_mfma_f32_16x16x32_bf16 v[10:13], v[142:145], v[228:231], v[10:13]
	s_setprio 0
	s_setprio 1
	v_mfma_f32_16x16x32_bf16 v[54:57], v[146:149], v[162:165], 0
	v_mfma_f32_16x16x32_bf16 v[50:53], v[154:157], v[162:165], 0
	v_mfma_f32_16x16x32_bf16 v[38:41], v[146:149], v[170:173], 0
	v_mfma_f32_16x16x32_bf16 v[34:37], v[154:157], v[170:173], 0
	v_mfma_f32_16x16x32_bf16 v[22:25], v[146:149], v[178:181], 0
	v_mfma_f32_16x16x32_bf16 v[18:21], v[154:157], v[178:181], 0
	v_mfma_f32_16x16x32_bf16 v[6:9], v[146:149], v[224:227], 0
	v_mfma_f32_16x16x32_bf16 v[2:5], v[154:157], v[224:227], 0
	v_mfma_f32_16x16x32_bf16 v[54:57], v[150:153], v[166:169], v[54:57]
	v_mfma_f32_16x16x32_bf16 v[50:53], v[158:161], v[166:169], v[50:53]
	v_mfma_f32_16x16x32_bf16 v[38:41], v[150:153], v[174:177], v[38:41]
	v_mfma_f32_16x16x32_bf16 v[34:37], v[158:161], v[174:177], v[34:37]
	v_mfma_f32_16x16x32_bf16 v[22:25], v[150:153], v[182:185], v[22:25]
	v_mfma_f32_16x16x32_bf16 v[18:21], v[158:161], v[182:185], v[18:21]
	v_mfma_f32_16x16x32_bf16 v[6:9], v[150:153], v[228:231], v[6:9]
	v_mfma_f32_16x16x32_bf16 v[2:5], v[158:161], v[228:231], v[2:5]
	s_barrier
	s_setprio 0
	s_add_i32 s89, 0, 0x18000
	s_add_i32 s90, 0, 0x1c000
	v_add_u32_e32 v142, s89, v214
	v_add_u32_e32 v158, s90, v214
	ds_read_b128 v[130:133], v142
	ds_read_b128 v[134:137], v142 offset:1024
	ds_read_b128 v[138:141], v142 offset:2048
	ds_read_b128 v[142:145], v142 offset:3072
	ds_read_b128 v[146:149], v158
	ds_read_b128 v[150:153], v158 offset:1024
	ds_read_b128 v[154:157], v158 offset:2048
	ds_read_b128 v[158:161], v158 offset:3072
	s_add_u32 s54, s68, 0x4000
	s_addc_u32 s55, s69, 0
	s_mov_b32 m0, s56
	ds_read_b128 v[162:165], v211 offset:32768
	ds_read_b128 v[166:169], v211 offset:33792
	ds_read_b128 v[170:173], v211 offset:34816
	ds_read_b128 v[174:177], v211 offset:35840
	ds_read_b128 v[178:181], v211 offset:36864
	ds_read_b128 v[182:185], v211 offset:37888
	ds_read_b128 v[224:227], v211 offset:38912
	ds_read_b128 v[228:231], v211 offset:39936
	global_load_lds_dwordx4 v186, s[54:55]
	s_mov_b32 m0, s57
	s_nop 0
	global_load_lds_dwordx4 v190, s[54:55]
	s_waitcnt vmcnt(8)
	s_waitcnt lgkmcnt(0)
	s_setprio 1
	s_barrier
	v_mfma_f32_16x16x32_bf16 v[126:129], v[130:133], v[162:165], v[126:129]
	v_mfma_f32_16x16x32_bf16 v[122:125], v[138:141], v[162:165], v[122:125]
	v_mfma_f32_16x16x32_bf16 v[110:113], v[130:133], v[170:173], v[110:113]
	v_mfma_f32_16x16x32_bf16 v[106:109], v[138:141], v[170:173], v[106:109]
	v_mfma_f32_16x16x32_bf16 v[94:97], v[130:133], v[178:181], v[94:97]
	v_mfma_f32_16x16x32_bf16 v[90:93], v[138:141], v[178:181], v[90:93]
	v_mfma_f32_16x16x32_bf16 v[78:81], v[130:133], v[224:227], v[78:81]
	v_mfma_f32_16x16x32_bf16 v[74:77], v[138:141], v[224:227], v[74:77]
	v_mfma_f32_16x16x32_bf16 v[126:129], v[134:137], v[166:169], v[126:129]
	v_mfma_f32_16x16x32_bf16 v[122:125], v[142:145], v[166:169], v[122:125]
	v_mfma_f32_16x16x32_bf16 v[110:113], v[134:137], v[174:177], v[110:113]
	v_mfma_f32_16x16x32_bf16 v[106:109], v[142:145], v[174:177], v[106:109]
	v_mfma_f32_16x16x32_bf16 v[94:97], v[134:137], v[182:185], v[94:97]
	v_mfma_f32_16x16x32_bf16 v[90:93], v[142:145], v[182:185], v[90:93]
	v_mfma_f32_16x16x32_bf16 v[78:81], v[134:137], v[228:231], v[78:81]
	v_mfma_f32_16x16x32_bf16 v[74:77], v[142:145], v[228:231], v[74:77]
	s_setprio 0
	s_setprio 1
	v_mfma_f32_16x16x32_bf16 v[118:121], v[146:149], v[162:165], v[118:121]
	v_mfma_f32_16x16x32_bf16 v[114:117], v[154:157], v[162:165], v[114:117]
	v_mfma_f32_16x16x32_bf16 v[102:105], v[146:149], v[170:173], v[102:105]
	v_mfma_f32_16x16x32_bf16 v[98:101], v[154:157], v[170:173], v[98:101]
	v_mfma_f32_16x16x32_bf16 v[86:89], v[146:149], v[178:181], v[86:89]
	v_mfma_f32_16x16x32_bf16 v[82:85], v[154:157], v[178:181], v[82:85]
	v_mfma_f32_16x16x32_bf16 v[70:73], v[146:149], v[224:227], v[70:73]
	v_mfma_f32_16x16x32_bf16 v[66:69], v[154:157], v[224:227], v[66:69]
	v_mfma_f32_16x16x32_bf16 v[118:121], v[150:153], v[166:169], v[118:121]
	v_mfma_f32_16x16x32_bf16 v[114:117], v[158:161], v[166:169], v[114:117]
	v_mfma_f32_16x16x32_bf16 v[102:105], v[150:153], v[174:177], v[102:105]
	v_mfma_f32_16x16x32_bf16 v[98:101], v[158:161], v[174:177], v[98:101]
	v_mfma_f32_16x16x32_bf16 v[86:89], v[150:153], v[182:185], v[86:89]
	v_mfma_f32_16x16x32_bf16 v[82:85], v[158:161], v[182:185], v[82:85]
	v_mfma_f32_16x16x32_bf16 v[70:73], v[150:153], v[228:231], v[70:73]
	v_mfma_f32_16x16x32_bf16 v[66:69], v[158:161], v[228:231], v[66:69]
	s_barrier
; #define PG8_STAGE(bufoff, gbase, voff) do { _Pragma("unroll") for (int _i = 0; _i < 2; ++_i) \
;         __builtin_amdgcn_global_load_lds((const unsigned*)((const char*)(gbase) + (voff)[_i]), (PG8_LAS unsigned*)(lds + (bufoff) + ldsw + _i * 8192), 16, 0, 0); } while (0)
; #define PG8_LDA(dst, b, h) do { _Pragma("unroll") for (int m = 0; m < 4; ++m) _Pragma("unroll") for (int k = 0; k < 2; ++k) dst[m][k] = *(const PG8_LAS bf16x8*)(lds + PG8_SA(b, h) + aoff + m * 2048 + k * 1024); } while (0)
; #define PG8_MMA(ai, bj, At, Bt) do { __builtin_amdgcn_s_setprio(1); _Pragma("unroll") for (int m = 0; m < 4; ++m) _Pragma("unroll") for (int n = 0; n < 2; ++n) _Pragma("unroll") for (int k = 0; k < 2; ++k) \
;         acc[ai][bj][m][n] = __builtin_amdgcn_mfma_f32_16x16x32_bf16(Bt[n][k], At[m][k], acc[ai][bj][m][n], 0, 0, 0); __builtin_amdgcn_s_setprio(0); } while (0)
; #define PG8_WAIT_V(n) asm volatile("s_waitcnt vmcnt(" #n ")" ::: "memory")
; #define PG8_WAIT_L(n) asm volatile("s_waitcnt lgkmcnt(" #n ")" ::: "memory")
; #define PG8_BAR __builtin_amdgcn_s_barrier()
; #define PG8_SCHED __builtin_amdgcn_sched_barrier(0)
; template <class Epi, class Sched, bool ALIGN_EPI = false, bool SP2 = false>
; __device__ __forceinline__ void gemm_phase(PG8_LAS unsigned char* lds, const Gemm g, const Sched& S, const Epi& E) {
;     ...
;             PG8_LDA(At, 1, 1); PG8_STAGE(PG8_SB(1, 0), b3, voffB); PG8_STAGE(PG8_SB(1, 1), b3 + hstepB, voffB); PG8_STAGE(PG8_SA(1, 0), a3, voffA);
;             PG8_WAIT_V(8); PG8_WAIT_L(0); PG8_BAR; PG8_MMA(1, 0, At, B0); PG8_MMA(1, 1, At, B1); PG8_BAR; PG8_SCHED;
	s_setprio 0
	s_add_u32 s54, s66, 0x8000
	s_addc_u32 s55, s67, 0
	s_add_i32 s68, s89, s0
	s_mov_b32 m0, s68
	ds_read_b128 v[162:165], v211 offset:49152
	ds_read_b128 v[166:169], v211 offset:50176
	ds_read_b128 v[170:173], v211 offset:51200
	ds_read_b128 v[174:177], v211 offset:52224
	ds_read_b128 v[178:181], v211 offset:53248
	ds_read_b128 v[182:185], v211 offset:54272
	ds_read_b128 v[224:227], v211 offset:55296
	ds_read_b128 v[228:231], v211 offset:56320
	global_load_lds_dwordx4 v188, s[54:55]
	s_add_i32 m0, s68, 0x2000
	v_lshl_add_u64 v[206:207], s[54:55], 0, v[192:193]
	s_add_u32 s54, s66, 0x9000
	s_addc_u32 s55, s67, 0
	s_add_i32 s66, s90, s0
	global_load_lds_dwordx4 v[206:207], off
	s_mov_b32 m0, s66
	s_nop 0
	global_load_lds_dwordx4 v188, s[54:55]
	s_add_i32 m0, s66, 0x2000
	s_nop 0
	global_load_lds_dwordx4 v192, s[54:55]
	s_mov_b32 m0, s71
	s_nop 0
	global_load_lds_dwordx4 v186, s[64:65]
	s_mov_b32 m0, s72
	s_nop 0
	global_load_lds_dwordx4 v190, s[64:65]
	s_waitcnt vmcnt(8)
	s_waitcnt lgkmcnt(0)
	s_setprio 1
	s_barrier
	v_mfma_f32_16x16x32_bf16 v[62:65], v[130:133], v[162:165], v[62:65]
	v_mfma_f32_16x16x32_bf16 v[58:61], v[138:141], v[162:165], v[58:61]
	v_mfma_f32_16x16x32_bf16 v[46:49], v[130:133], v[170:173], v[46:49]
	v_mfma_f32_16x16x32_bf16 v[42:45], v[138:141], v[170:173], v[42:45]
	v_mfma_f32_16x16x32_bf16 v[30:33], v[130:133], v[178:181], v[30:33]
	v_mfma_f32_16x16x32_bf16 v[26:29], v[138:141], v[178:181], v[26:29]
	v_mfma_f32_16x16x32_bf16 v[14:17], v[130:133], v[224:227], v[14:17]
	v_mfma_f32_16x16x32_bf16 v[10:13], v[138:141], v[224:227], v[10:13]
	v_mfma_f32_16x16x32_bf16 v[62:65], v[134:137], v[166:169], v[62:65]
	v_mfma_f32_16x16x32_bf16 v[58:61], v[142:145], v[166:169], v[58:61]
	v_mfma_f32_16x16x32_bf16 v[46:49], v[134:137], v[174:177], v[46:49]
	v_mfma_f32_16x16x32_bf16 v[42:45], v[142:145], v[174:177], v[42:45]
	v_mfma_f32_16x16x32_bf16 v[30:33], v[134:137], v[182:185], v[30:33]
	v_mfma_f32_16x16x32_bf16 v[26:29], v[142:145], v[182:185], v[26:29]
	v_mfma_f32_16x16x32_bf16 v[14:17], v[134:137], v[228:231], v[14:17]
	v_mfma_f32_16x16x32_bf16 v[10:13], v[142:145], v[228:231], v[10:13]
	s_setprio 0
	s_setprio 1
	v_mfma_f32_16x16x32_bf16 v[54:57], v[146:149], v[162:165], v[54:57]
	v_mfma_f32_16x16x32_bf16 v[50:53], v[154:157], v[162:165], v[50:53]
	v_mfma_f32_16x16x32_bf16 v[38:41], v[146:149], v[170:173], v[38:41]
	v_mfma_f32_16x16x32_bf16 v[34:37], v[154:157], v[170:173], v[34:37]
	v_mfma_f32_16x16x32_bf16 v[22:25], v[146:149], v[178:181], v[22:25]
	v_mfma_f32_16x16x32_bf16 v[18:21], v[154:157], v[178:181], v[18:21]
	v_mfma_f32_16x16x32_bf16 v[6:9], v[146:149], v[224:227], v[6:9]
	v_mfma_f32_16x16x32_bf16 v[2:5], v[154:157], v[224:227], v[2:5]
	v_mfma_f32_16x16x32_bf16 v[54:57], v[150:153], v[166:169], v[54:57]
	v_mfma_f32_16x16x32_bf16 v[50:53], v[158:161], v[166:169], v[50:53]
	v_mfma_f32_16x16x32_bf16 v[38:41], v[150:153], v[174:177], v[38:41]
	v_mfma_f32_16x16x32_bf16 v[34:37], v[158:161], v[174:177], v[34:37]
	v_mfma_f32_16x16x32_bf16 v[22:25], v[150:153], v[182:185], v[22:25]
	v_mfma_f32_16x16x32_bf16 v[18:21], v[158:161], v[182:185], v[18:21]
	v_mfma_f32_16x16x32_bf16 v[6:9], v[150:153], v[228:231], v[6:9]
	v_mfma_f32_16x16x32_bf16 v[2:5], v[158:161], v[228:231], v[2:5]
	s_barrier
	s_setprio 0
	s_add_i32 s53, s53, 2
	s_add_u32 s50, s50, 0x10000
	s_addc_u32 s51, s51, 0
	s_add_u32 s49, s49, 0x10000
	s_addc_u32 s52, s52, 0
	.p2align 6
